# P8 gate phase: fnet-half YG loads for all 8 tokens issued at the item top (one round trip instead of eight)
# baseline (speedup 1.0000x reference)
.LBB0_777:
	s_and_b32 s26, s25, 1
	s_and_b32 s8, s19, 0xffffffc0
	v_add_u32_e32 v66, s8, v1
	s_lshl_b32 s0, s26, 11
	s_add_u32 s0, s3, s0
	v_ashrrev_i32_e32 v67, 31, v66
	s_addc_u32 s1, s18, 0
	v_lshlrev_b64 v[96:97], 12, v[66:67]
	v_lshl_add_u64 v[2:3], s[0:1], 0, v[96:97]
	v_lshl_add_u64 v[2:3], v[2:3], 0, v[74:75]
	global_load_dwordx4 v[62:65], v[2:3], off nt
	global_load_dwordx4 v[58:61], v[2:3], off offset:1024 nt
	v_or_b32_e32 v2, 1, v66
	v_ashrrev_i32_e32 v3, 31, v2
	v_lshlrev_b64 v[2:3], 12, v[2:3]
	v_lshl_add_u64 v[2:3], s[0:1], 0, v[2:3]
	v_lshl_add_u64 v[2:3], v[2:3], 0, v[74:75]
	global_load_dwordx4 v[54:57], v[2:3], off nt
	global_load_dwordx4 v[50:53], v[2:3], off offset:1024 nt
	v_or_b32_e32 v2, 2, v66
	v_ashrrev_i32_e32 v3, 31, v2
	v_lshlrev_b64 v[2:3], 12, v[2:3]
	v_lshl_add_u64 v[2:3], s[0:1], 0, v[2:3]
	v_lshl_add_u64 v[2:3], v[2:3], 0, v[74:75]
	global_load_dwordx4 v[46:49], v[2:3], off nt
	global_load_dwordx4 v[42:45], v[2:3], off offset:1024 nt
	v_or_b32_e32 v2, 3, v66
	v_ashrrev_i32_e32 v3, 31, v2
	v_lshlrev_b64 v[2:3], 12, v[2:3]
	v_lshl_add_u64 v[2:3], s[0:1], 0, v[2:3]
	v_lshl_add_u64 v[2:3], v[2:3], 0, v[74:75]
	global_load_dwordx4 v[38:41], v[2:3], off nt
	global_load_dwordx4 v[34:37], v[2:3], off offset:1024 nt
	v_or_b32_e32 v2, 4, v66
	v_ashrrev_i32_e32 v3, 31, v2
	v_lshlrev_b64 v[2:3], 12, v[2:3]
	v_lshl_add_u64 v[2:3], s[0:1], 0, v[2:3]
	v_lshl_add_u64 v[2:3], v[2:3], 0, v[74:75]
	global_load_dwordx4 v[30:33], v[2:3], off nt
	global_load_dwordx4 v[26:29], v[2:3], off offset:1024 nt
	v_or_b32_e32 v2, 5, v66
	v_ashrrev_i32_e32 v3, 31, v2
	v_lshlrev_b64 v[2:3], 12, v[2:3]
	v_lshl_add_u64 v[2:3], s[0:1], 0, v[2:3]
	v_lshl_add_u64 v[2:3], v[2:3], 0, v[74:75]
	global_load_dwordx4 v[22:25], v[2:3], off nt
	global_load_dwordx4 v[18:21], v[2:3], off offset:1024 nt
	v_or_b32_e32 v2, 6, v66
	v_ashrrev_i32_e32 v3, 31, v2
	v_lshlrev_b64 v[2:3], 12, v[2:3]
	v_lshl_add_u64 v[2:3], s[0:1], 0, v[2:3]
	v_lshl_add_u64 v[2:3], v[2:3], 0, v[74:75]
	global_load_dwordx4 v[14:17], v[2:3], off nt
	global_load_dwordx4 v[10:13], v[2:3], off offset:1024 nt
	v_or_b32_e32 v2, 7, v66
	v_ashrrev_i32_e32 v3, 31, v2
	v_lshlrev_b64 v[2:3], 12, v[2:3]
	v_lshl_add_u64 v[2:3], s[0:1], 0, v[2:3]
	v_lshl_add_u64 v[2:3], v[2:3], 0, v[74:75]
	global_load_dwordx4 v[6:9], v[2:3], off nt
	s_nop 0
	global_load_dwordx4 v[2:5], v[2:3], off offset:1024 nt
	s_bitcmp1_b32 s25, 0
	s_cselect_b64 s[10:11], -1, 0
	s_and_b64 vcc, exec, s[10:11]
	s_cbranch_vccz .Lp8_hy
	v_lshlrev_b64 v[222:223], 11, v[66:67]
	v_lshl_add_u64 v[222:223], s[6:7], 0, v[222:223]
	v_lshl_add_u64 v[222:223], v[222:223], 0, v[74:75]
	s_mov_b64 s[100:101], 0x1000
	global_load_dwordx4 v[154:157], v[222:223], off nt
	global_load_dwordx4 v[158:161], v[222:223], off offset:1024 nt
	global_load_dwordx4 v[162:165], v[222:223], off offset:2048 nt
	global_load_dwordx4 v[166:169], v[222:223], off offset:3072 nt
	v_lshl_add_u64 v[222:223], v[222:223], 0, s[100:101]
	global_load_dwordx4 v[170:173], v[222:223], off nt
	global_load_dwordx4 v[174:177], v[222:223], off offset:1024 nt
	global_load_dwordx4 v[178:181], v[222:223], off offset:2048 nt
	global_load_dwordx4 v[182:185], v[222:223], off offset:3072 nt
	v_lshl_add_u64 v[222:223], v[222:223], 0, s[100:101]
	global_load_dwordx4 v[186:189], v[222:223], off nt
	global_load_dwordx4 v[190:193], v[222:223], off offset:1024 nt
	global_load_dwordx4 v[194:197], v[222:223], off offset:2048 nt
	global_load_dwordx4 v[202:205], v[222:223], off offset:3072 nt
	v_lshl_add_u64 v[222:223], v[222:223], 0, s[100:101]
	global_load_dwordx4 v[206:209], v[222:223], off nt
	global_load_dwordx4 v[210:213], v[222:223], off offset:1024 nt
	global_load_dwordx4 v[214:217], v[222:223], off offset:2048 nt
	global_load_dwordx4 v[218:221], v[222:223], off offset:3072 nt
	s_branch .LBB0_779
.Lp8_hy:
	s_ashr_i32 s9, s8, 31
	s_lshl_b64 s[16:17], s[8:9], 1
	v_lshl_add_u64 v[72:73], v[76:77], 0, s[16:17]
	v_lshl_add_u64 v[94:95], v[78:79], 0, s[16:17]
	global_load_dwordx4 v[68:71], v[72:73], off nt
	global_load_dwordx4 v[140:143], v[94:95], off nt
	v_add_co_u32_e64 v94, s[0:1], s21, v94
	v_lshl_add_u64 v[98:99], v[80:81], 0, s[16:17]
	s_nop 0
	v_addc_co_u32_e64 v95, s[0:1], 0, v95, s[0:1]
	global_load_dwordx4 v[148:151], v[98:99], off nt
	global_load_dwordx4 v[152:155], v[94:95], off nt
	v_add_co_u32_e64 v94, s[0:1], s21, v98
	v_add_co_u32_e32 v72, vcc, 0x10000, v72
	s_nop 0
	v_addc_co_u32_e64 v95, s[0:1], 0, v99, s[0:1]
	v_addc_co_u32_e32 v73, vcc, 0, v73, vcc
	global_load_dwordx4 v[156:159], v[94:95], off nt
	global_load_dwordx4 v[160:163], v[72:73], off nt
	v_lshl_add_u64 v[72:73], v[82:83], 0, s[16:17]
	v_add_co_u32_e32 v144, vcc, s21, v72
	v_lshl_add_u64 v[94:95], v[84:85], 0, s[16:17]
	s_nop 0
	v_addc_co_u32_e32 v145, vcc, 0, v73, vcc
	global_load_dwordx4 v[164:167], v[72:73], off nt
	global_load_dwordx4 v[168:171], v[144:145], off nt
	v_add_co_u32_e32 v72, vcc, s21, v94
	v_lshl_add_u64 v[98:99], v[86:87], 0, s[16:17]
	s_nop 0
	v_addc_co_u32_e32 v73, vcc, 0, v95, vcc
	v_add_co_u32_e32 v144, vcc, s21, v98
	s_waitcnt vmcnt(0)
	v_and_b32_e32 v139, 0xffff, v141
	v_addc_co_u32_e32 v145, vcc, 0, v99, vcc
	global_load_dwordx4 v[172:175], v[94:95], off nt
	global_load_dwordx4 v[176:179], v[72:73], off nt
	global_load_dwordx4 v[180:183], v[98:99], off nt
	global_load_dwordx4 v[184:187], v[144:145], off nt
	v_and_b32_e32 v72, 0xffff, v68
	v_lshrrev_b32_e32 v68, 16, v68
	v_and_b32_e32 v73, 0xffff, v69
	v_lshrrev_b32_e32 v69, 16, v69
	v_and_b32_e32 v94, 0xffff, v70
	v_lshrrev_b32_e32 v70, 16, v70
	v_and_b32_e32 v95, 0xffff, v71
	v_lshrrev_b32_e32 v71, 16, v71
	v_and_b32_e32 v98, 0xffff, v140
	v_lshrrev_b32_e32 v99, 16, v140
	v_lshrrev_b32_e32 v140, 16, v141
	v_and_b32_e32 v141, 0xffff, v142
	v_lshrrev_b32_e32 v142, 16, v142
	v_and_b32_e32 v144, 0xffff, v143
	v_lshrrev_b32_e32 v143, 16, v143
	v_lshl_or_b32 v72, v160, 16, v72
	v_and_or_b32 v68, v160, s22, v68
	v_lshl_or_b32 v73, v161, 16, v73
	v_lshl_or_b32 v98, v152, 16, v98
	v_and_or_b32 v99, v152, s22, v99
	v_lshl_or_b32 v139, v153, 16, v139
	v_and_or_b32 v140, v153, s22, v140
	v_lshl_or_b32 v141, v154, 16, v141
	v_and_or_b32 v142, v154, s22, v142
	v_lshl_or_b32 v144, v155, 16, v144
	v_and_or_b32 v143, v155, s22, v143
	v_and_or_b32 v69, v161, s22, v69
	v_lshl_or_b32 v94, v162, 16, v94
	v_and_or_b32 v70, v162, s22, v70
	v_lshl_or_b32 v95, v163, 16, v95
	v_and_or_b32 v71, v163, s22, v71
	ds_write2st64_b32 v105, v72, v73 offset1:16
	ds_write2st64_b32 v106, v68, v69 offset0:8 offset1:24
	ds_write2st64_b32 v105, v94, v95 offset0:32 offset1:48
	ds_write2st64_b32 v106, v70, v71 offset0:40 offset1:56
	ds_write2st64_b32 v107, v98, v139 offset1:16
	ds_write2st64_b32 v108, v99, v140 offset0:8 offset1:24
	ds_write2st64_b32 v107, v141, v144 offset0:32 offset1:48
	ds_write2st64_b32 v108, v142, v143 offset0:40 offset1:56
	v_lshrrev_b32_e32 v68, 16, v148
	v_and_b32_e32 v145, 0xffff, v148
	v_and_or_b32 v94, v156, s22, v68
	v_and_b32_e32 v68, 0xffff, v149
	v_lshl_or_b32 v145, v156, 16, v145
	v_lshl_or_b32 v68, v157, 16, v68
	ds_write2st64_b32 v109, v145, v68 offset1:16
	v_lshrrev_b32_e32 v68, 16, v149
	v_and_or_b32 v95, v157, s22, v68
	v_lshl_add_u64 v[68:69], v[88:89], 0, s[16:17]
	v_add_co_u32_e32 v72, vcc, s21, v68
	s_nop 1
	v_addc_co_u32_e32 v73, vcc, 0, v69, vcc
	global_load_dwordx4 v[68:71], v[68:69], off nt
	s_nop 0
	global_load_dwordx4 v[140:143], v[72:73], off nt
	ds_write2st64_b32 v110, v94, v95 offset0:8 offset1:24
	v_and_b32_e32 v72, 0xffff, v150
	v_and_b32_e32 v94, 0xffff, v151
	v_lshl_or_b32 v72, v158, 16, v72
	v_lshl_or_b32 v94, v159, 16, v94
	v_lshrrev_b32_e32 v73, 16, v150
	ds_write2st64_b32 v109, v72, v94 offset0:32 offset1:48
	v_lshrrev_b32_e32 v72, 16, v151
	v_and_or_b32 v73, v158, s22, v73
	v_and_or_b32 v72, v159, s22, v72
	ds_write2st64_b32 v110, v73, v72 offset0:40 offset1:56
	v_and_b32_e32 v72, 0xffff, v164
	v_lshl_or_b32 v98, v168, 16, v72
	v_lshl_add_u64 v[72:73], v[90:91], 0, s[16:17]
	v_add_co_u32_e32 v94, vcc, s21, v72
	s_nop 1
	v_addc_co_u32_e32 v95, vcc, 0, v73, vcc
	global_load_dwordx4 v[148:151], v[72:73], off nt
	global_load_dwordx4 v[152:155], v[94:95], off nt
	v_and_b32_e32 v73, 0xffff, v165
	v_lshl_or_b32 v73, v169, 16, v73
	v_lshrrev_b32_e32 v72, 16, v164
	ds_write2st64_b32 v111, v98, v73 offset1:16
	v_lshrrev_b32_e32 v73, 16, v165
	v_and_or_b32 v72, v168, s22, v72
	v_and_or_b32 v73, v169, s22, v73
	ds_write2st64_b32 v112, v72, v73 offset0:8 offset1:24
	v_and_b32_e32 v72, 0xffff, v166
	v_and_b32_e32 v94, 0xffff, v167
	v_lshl_or_b32 v72, v170, 16, v72
	v_lshl_or_b32 v94, v171, 16, v94
	v_lshrrev_b32_e32 v73, 16, v166
	ds_write2st64_b32 v111, v72, v94 offset0:32 offset1:48
	v_lshrrev_b32_e32 v72, 16, v167
	v_and_or_b32 v73, v170, s22, v73
	v_and_or_b32 v72, v171, s22, v72
	ds_write2st64_b32 v112, v73, v72 offset0:40 offset1:56
	s_waitcnt vmcnt(0)
	v_and_b32_e32 v72, 0xffff, v172
	v_and_b32_e32 v94, 0xffff, v173
	v_lshl_or_b32 v72, v176, 16, v72
	v_lshl_or_b32 v94, v177, 16, v94
	v_lshrrev_b32_e32 v73, 16, v172
	ds_write2st64_b32 v113, v72, v94 offset1:16
	v_lshrrev_b32_e32 v72, 16, v173
	v_and_or_b32 v73, v176, s22, v73
	v_and_or_b32 v72, v177, s22, v72
	ds_write2st64_b32 v114, v73, v72 offset0:8 offset1:24
	v_and_b32_e32 v72, 0xffff, v174
	v_and_b32_e32 v94, 0xffff, v175
	v_lshl_or_b32 v72, v178, 16, v72
	v_lshl_or_b32 v94, v179, 16, v94
	v_lshrrev_b32_e32 v73, 16, v174
	ds_write2st64_b32 v113, v72, v94 offset0:32 offset1:48
	v_lshrrev_b32_e32 v72, 16, v175
	v_and_or_b32 v73, v178, s22, v73
	v_and_or_b32 v72, v179, s22, v72
	ds_write2st64_b32 v114, v73, v72 offset0:40 offset1:56
	v_and_b32_e32 v72, 0xffff, v180
	v_and_b32_e32 v94, 0xffff, v181
	v_lshl_or_b32 v72, v184, 16, v72
	v_lshl_or_b32 v94, v185, 16, v94
	v_lshrrev_b32_e32 v73, 16, v180
	ds_write2st64_b32 v115, v72, v94 offset1:16
	v_lshrrev_b32_e32 v72, 16, v181
	v_and_or_b32 v73, v184, s22, v73
	v_and_or_b32 v72, v185, s22, v72
	ds_write2st64_b32 v116, v73, v72 offset0:8 offset1:24
	v_and_b32_e32 v72, 0xffff, v182
	v_and_b32_e32 v94, 0xffff, v183
	v_lshl_or_b32 v72, v186, 16, v72
	v_lshl_or_b32 v94, v187, 16, v94
	v_lshrrev_b32_e32 v73, 16, v182
	ds_write2st64_b32 v115, v72, v94 offset0:32 offset1:48
	v_lshrrev_b32_e32 v72, 16, v183
	v_and_or_b32 v73, v186, s22, v73
	v_and_or_b32 v72, v187, s22, v72
	ds_write2st64_b32 v116, v73, v72 offset0:40 offset1:56
	v_and_b32_e32 v72, 0xffff, v68
	v_lshrrev_b32_e32 v68, 16, v68
	v_and_b32_e32 v73, 0xffff, v69
	v_lshrrev_b32_e32 v69, 16, v69
	v_and_or_b32 v68, v140, s22, v68
	v_and_or_b32 v69, v141, s22, v69
	ds_write2st64_b32 v118, v68, v69 offset0:8 offset1:24
	v_and_b32_e32 v68, 0xffff, v70
	v_lshrrev_b32_e32 v69, 16, v70
	v_and_b32_e32 v70, 0xffff, v71
	v_lshl_or_b32 v68, v142, 16, v68
	v_lshl_or_b32 v70, v143, 16, v70
	ds_write2st64_b32 v117, v68, v70 offset0:32 offset1:48
	v_lshrrev_b32_e32 v68, 16, v71
	v_and_or_b32 v69, v142, s22, v69
	v_and_or_b32 v68, v143, s22, v68
	ds_write2st64_b32 v118, v69, v68 offset0:40 offset1:56
	v_lshl_or_b32 v72, v140, 16, v72
	v_lshl_or_b32 v73, v141, 16, v73
	ds_write2st64_b32 v117, v72, v73 offset1:16
	v_and_b32_e32 v68, 0xffff, v148
	v_and_b32_e32 v70, 0xffff, v149
	v_lshl_or_b32 v68, v152, 16, v68
	v_lshl_or_b32 v70, v153, 16, v70
	v_lshrrev_b32_e32 v69, 16, v148
	ds_write2st64_b32 v119, v68, v70 offset1:16
	v_lshrrev_b32_e32 v68, 16, v149
	v_and_or_b32 v69, v152, s22, v69
	v_and_or_b32 v68, v153, s22, v68
	ds_write2st64_b32 v120, v69, v68 offset0:8 offset1:24
	v_and_b32_e32 v68, 0xffff, v150
	v_and_b32_e32 v70, 0xffff, v151
	v_lshl_or_b32 v68, v154, 16, v68
	v_lshl_or_b32 v70, v155, 16, v70
	v_lshrrev_b32_e32 v69, 16, v150
	ds_write2st64_b32 v119, v68, v70 offset0:32 offset1:48
	v_lshrrev_b32_e32 v68, 16, v151
	v_and_or_b32 v69, v154, s22, v69
	v_and_or_b32 v68, v155, s22, v68
	ds_write2st64_b32 v120, v69, v68 offset0:40 offset1:56
.LBB0_779:
	v_lshlrev_b64 v[66:67], 11, v[66:67]
	v_lshl_add_u64 v[98:99], s[6:7], 0, v[66:67]
	v_cndmask_b32_e64 v66, 0, 1, s[10:11]
	v_cmp_ne_u32_e64 s[0:1], 1, v66
	s_andn2_b64 vcc, exec, s[10:11]
	s_mov_b64 s[10:11], -1
	s_waitcnt lgkmcnt(0)
	s_barrier
	s_cbranch_vccnz .LBB0_781
	v_lshl_add_u64 v[66:67], v[98:99], 0, v[74:75]
	s_waitcnt vmcnt(0)
	v_mov_b64_e32 v[70:71], v[154:155]
	v_mov_b64_e32 v[72:73], v[156:157]
	s_cbranch_execnz .LBB0_783
	s_branch .LBB0_782

.LBB0_783:
	s_mov_b64 s[10:11], -1
	s_and_b64 vcc, exec, s[0:1]
	v_lshlrev_b32_e32 v94, 2, v92
	s_cbranch_vccnz .LBB0_785
	v_mov_b32_e32 v95, v75
	v_lshl_add_u64 v[66:67], v[98:99], 0, v[94:95]
	v_mov_b64_e32 v[66:67], v[158:159]
	v_mov_b64_e32 v[68:69], v[160:161]
	s_cbranch_execz .LBB0_786
	s_branch .LBB0_787

.LBB0_787:
	s_waitcnt vmcnt(15)
	v_lshlrev_b32_e32 v98, 16, v62
	v_mul_f32_e32 v95, 0xbfb8aa3b, v98
	v_exp_f32_e32 v95, v95
	v_and_b32_e32 v62, 0xffff0000, v62
	v_lshlrev_b32_e32 v99, 16, v63
	v_mul_f32_e32 v139, 0xbfb8aa3b, v62
	v_add_f32_e32 v95, 1.0, v95
	v_rcp_f32_e32 v140, v95
	v_exp_f32_e32 v95, v139
	v_mul_f32_e32 v139, 0xbfb8aa3b, v99
	v_exp_f32_e32 v139, v139
	v_and_b32_e32 v63, 0xffff0000, v63
	v_add_f32_e32 v95, 1.0, v95
	v_rcp_f32_e32 v142, v95
	v_add_f32_e32 v95, 1.0, v139
	v_rcp_f32_e32 v141, v95
	v_mul_f32_e32 v95, 0xbfb8aa3b, v63
	v_exp_f32_e32 v95, v95
	s_waitcnt vmcnt(0) lgkmcnt(0)
	v_lshlrev_b32_e32 v145, 16, v71
	v_lshlrev_b32_e32 v144, 16, v70
	v_and_b32_e32 v71, 0xffff0000, v71
	v_add_f32_e32 v95, 1.0, v95
	v_rcp_f32_e32 v143, v95
	v_and_b32_e32 v70, 0xffff0000, v70
	v_pk_mul_f32 v[98:99], v[140:141], v[98:99]
	v_lshlrev_b32_e32 v149, 16, v73
	v_pk_mul_f32 v[62:63], v[142:143], v[62:63]
	v_pk_mul_f32 v[98:99], v[98:99], v[144:145]
	v_pk_mul_f32 v[62:63], v[62:63], v[70:71]
	v_lshlrev_b32_e32 v70, 16, v64
	v_mul_f32_e32 v71, 0xbfb8aa3b, v70
	v_exp_f32_e32 v95, v71
	v_and_b32_e32 v64, 0xffff0000, v64
	v_lshlrev_b32_e32 v71, 16, v65
	v_mul_f32_e32 v139, 0xbfb8aa3b, v71
	v_add_f32_e32 v95, 1.0, v95
	v_rcp_f32_e32 v142, v95
	v_mul_f32_e32 v95, 0xbfb8aa3b, v64
	v_exp_f32_e32 v95, v95
	v_exp_f32_e32 v139, v139
	v_and_b32_e32 v65, 0xffff0000, v65
	v_lshlrev_b32_e32 v148, 16, v72
	v_add_f32_e32 v95, 1.0, v95
	v_rcp_f32_e32 v144, v95
	v_add_f32_e32 v95, 1.0, v139
	v_rcp_f32_e32 v143, v95
	v_mul_f32_e32 v95, 0xbfb8aa3b, v65
	v_exp_f32_e32 v95, v95
	v_and_b32_e32 v73, 0xffff0000, v73
	v_and_b32_e32 v72, 0xffff0000, v72
	v_pk_mul_f32 v[70:71], v[142:143], v[70:71]
	v_add_f32_e32 v95, 1.0, v95
	v_rcp_f32_e32 v145, v95
	v_pk_mul_f32 v[70:71], v[70:71], v[148:149]
	v_lshlrev_b32_e32 v151, 16, v67
	v_lshlrev_b32_e32 v150, 16, v66
	v_pk_mul_f32 v[64:65], v[144:145], v[64:65]
	v_and_b32_e32 v67, 0xffff0000, v67
	v_pk_mul_f32 v[64:65], v[64:65], v[72:73]
	v_lshlrev_b32_e32 v72, 16, v58
	v_mul_f32_e32 v73, 0xbfb8aa3b, v72
	v_exp_f32_e32 v95, v73
	v_and_b32_e32 v58, 0xffff0000, v58
	v_lshlrev_b32_e32 v73, 16, v59
	v_mul_f32_e32 v139, 0xbfb8aa3b, v73
	v_add_f32_e32 v95, 1.0, v95
	v_rcp_f32_e32 v144, v95
	v_mul_f32_e32 v95, 0xbfb8aa3b, v58
	v_exp_f32_e32 v95, v95
	v_exp_f32_e32 v139, v139
	v_and_b32_e32 v59, 0xffff0000, v59
	v_and_b32_e32 v66, 0xffff0000, v66
	v_add_f32_e32 v95, 1.0, v95
	v_rcp_f32_e32 v148, v95
	v_add_f32_e32 v95, 1.0, v139
	v_rcp_f32_e32 v145, v95
	v_mul_f32_e32 v95, 0xbfb8aa3b, v59
	v_exp_f32_e32 v95, v95
	v_pk_mul_f32 v[140:141], v[62:63], v[62:63]
	v_pk_mul_f32 v[72:73], v[144:145], v[72:73]
	v_lshlrev_b32_e32 v153, 16, v69
	v_add_f32_e32 v95, 1.0, v95
	v_rcp_f32_e32 v149, v95
	v_pk_mul_f32 v[72:73], v[72:73], v[150:151]
	v_lshlrev_b32_e32 v152, 16, v68
	v_pk_fma_f32 v[140:141], v[98:99], v[98:99], v[140:141]
	v_pk_mul_f32 v[58:59], v[148:149], v[58:59]
	v_pk_mul_f32 v[142:143], v[64:65], v[64:65]
	v_pk_mul_f32 v[66:67], v[58:59], v[66:67]
	v_lshlrev_b32_e32 v58, 16, v60
	v_mul_f32_e32 v59, 0xbfb8aa3b, v58
	v_exp_f32_e32 v95, v59
	v_and_b32_e32 v60, 0xffff0000, v60
	v_lshlrev_b32_e32 v59, 16, v61
	v_mul_f32_e32 v139, 0xbfb8aa3b, v59
	v_add_f32_e32 v95, 1.0, v95
	v_rcp_f32_e32 v148, v95
	v_mul_f32_e32 v95, 0xbfb8aa3b, v60
	v_exp_f32_e32 v95, v95
	v_exp_f32_e32 v139, v139
	v_and_b32_e32 v61, 0xffff0000, v61
	v_pk_fma_f32 v[142:143], v[70:71], v[70:71], v[142:143]
	v_add_f32_e32 v95, 1.0, v95
	v_rcp_f32_e32 v150, v95
	v_add_f32_e32 v95, 1.0, v139
	v_rcp_f32_e32 v149, v95
	v_mul_f32_e32 v95, 0xbfb8aa3b, v61
	v_exp_f32_e32 v95, v95
	v_pk_mul_f32 v[144:145], v[66:67], v[66:67]
	v_pk_mul_f32 v[58:59], v[148:149], v[58:59]
	v_pk_fma_f32 v[144:145], v[72:73], v[72:73], v[144:145]
	v_add_f32_e32 v95, 1.0, v95
	v_rcp_f32_e32 v151, v95
	v_pk_mul_f32 v[148:149], v[58:59], v[152:153]
	v_and_b32_e32 v59, 0xffff0000, v69
	v_and_b32_e32 v58, 0xffff0000, v68
	v_pk_mul_f32 v[60:61], v[150:151], v[60:61]
	s_lshl_b32 s9, s26, 9
	v_pk_mul_f32 v[68:69], v[60:61], v[58:59]
	v_add_f32_e32 v60, v140, v141
	v_add_f32_e32 v60, v142, v60
	v_add_f32_e32 v60, v143, v60
	v_pk_mul_f32 v[58:59], v[68:69], v[68:69]
	v_add_f32_e32 v60, v60, v144
	v_pk_fma_f32 v[58:59], v[148:149], v[148:149], v[58:59]
	v_add_f32_e32 v60, v145, v60
	v_add_f32_e32 v58, v58, v60
	v_add_f32_e32 v58, v59, v58
	ds_bpermute_b32 v59, v93, v58
	s_lshl_b32 s9, s9, 2
	s_add_u32 s10, s56, s9
	s_addc_u32 s11, s57, 0
	s_mov_b64 s[16:17], -1
	s_waitcnt lgkmcnt(0)
	v_add_f32_e32 v58, v58, v59
	ds_bpermute_b32 v59, v100, v58
	s_waitcnt lgkmcnt(0)
	v_add_f32_e32 v58, v58, v59
	ds_bpermute_b32 v59, v101, v58
	s_waitcnt lgkmcnt(0)
	v_add_f32_e32 v58, v58, v59
	ds_bpermute_b32 v59, v102, v58
	s_waitcnt lgkmcnt(0)
	v_add_f32_e32 v58, v58, v59
	ds_bpermute_b32 v59, v103, v58
	s_waitcnt lgkmcnt(0)
	v_add_f32_e32 v58, v58, v59
	ds_bpermute_b32 v59, v104, v58
	s_waitcnt lgkmcnt(0)
	v_add_f32_e32 v58, v58, v59
	v_fmamk_f32 v58, v58, 0x3a800000, v138
	v_mul_f32_e32 v59, 0x4b800000, v58
	v_cmp_gt_f32_e32 vcc, s23, v58
	s_nop 1
	v_cndmask_b32_e32 v58, v58, v59, vcc
	v_rsq_f32_e32 v60, v58
	v_lshl_add_u64 v[58:59], s[10:11], 0, v[96:97]
	v_lshl_add_u64 v[96:97], v[58:59], 0, v[74:75]
	v_mul_f32_e32 v58, 0x45800000, v60
	v_cndmask_b32_e32 v140, v60, v58, vcc
	v_pk_mul_f32 v[60:61], v[62:63], v[140:141] op_sel_hi:[1,0]
	v_pk_mul_f32 v[64:65], v[64:65], v[140:141] op_sel_hi:[1,0]
	v_pk_mul_f32 v[58:59], v[98:99], v[140:141] op_sel_hi:[1,0]
	v_pk_mul_f32 v[62:63], v[70:71], v[140:141] op_sel_hi:[1,0]
	v_bfe_u32 v70, v65, 16, 1
	v_bfe_u32 v71, v64, 16, 1
	v_bfe_u32 v95, v61, 16, 1
	v_bfe_u32 v98, v60, 16, 1
	v_add3_u32 v98, v60, v98, s24
	v_add3_u32 v95, v61, v95, s24
	v_add3_u32 v60, v64, v71, s24
	v_add3_u32 v61, v65, v70, s24
	v_bfe_u32 v64, v58, 16, 1
	v_bfe_u32 v65, v59, 16, 1
	v_bfe_u32 v70, v62, 16, 1
	v_bfe_u32 v71, v63, 16, 1
	v_add3_u32 v63, v63, v71, s24
	v_add3_u32 v62, v62, v70, s24
	v_add3_u32 v59, v59, v65, s24
	v_add3_u32 v58, v58, v64, s24
	v_lshrrev_b32_e32 v58, 16, v58
	v_lshrrev_b32_e32 v59, 16, v59
	v_lshrrev_b32_e32 v62, 16, v62
	v_lshrrev_b32_e32 v63, 16, v63
	v_and_or_b32 v61, v61, s22, v63
	v_and_or_b32 v60, v60, s22, v62
	v_and_or_b32 v59, v95, s22, v59
	v_and_or_b32 v58, v98, s22, v58
	global_store_dwordx4 v[96:97], v[58:61], off
	v_pk_mul_f32 v[64:65], v[68:69], v[140:141] op_sel_hi:[1,0]
	v_pk_mul_f32 v[62:63], v[148:149], v[140:141] op_sel_hi:[1,0]
	v_pk_mul_f32 v[60:61], v[66:67], v[140:141] op_sel_hi:[1,0]
	v_pk_mul_f32 v[58:59], v[72:73], v[140:141] op_sel_hi:[1,0]
	v_bfe_u32 v66, v65, 16, 1
	v_bfe_u32 v67, v64, 16, 1
	v_bfe_u32 v68, v61, 16, 1
	v_bfe_u32 v69, v60, 16, 1
	v_add3_u32 v69, v60, v69, s24
	v_add3_u32 v68, v61, v68, s24
	v_add3_u32 v60, v64, v67, s24
	v_add3_u32 v61, v65, v66, s24
	v_bfe_u32 v64, v58, 16, 1
	v_bfe_u32 v65, v59, 16, 1
	v_bfe_u32 v66, v62, 16, 1
	v_bfe_u32 v67, v63, 16, 1
	v_add3_u32 v63, v63, v67, s24
	v_add3_u32 v62, v62, v66, s24
	v_add3_u32 v59, v59, v65, s24
	v_add3_u32 v58, v58, v64, s24
	v_lshrrev_b32_e32 v58, 16, v58
	v_lshrrev_b32_e32 v59, 16, v59
	v_lshrrev_b32_e32 v62, 16, v62
	v_lshrrev_b32_e32 v63, 16, v63
	v_add_u32_e32 v66, s8, v124
	v_and_or_b32 v61, v61, s22, v63
	v_and_or_b32 v60, v60, s22, v62
	v_and_or_b32 v59, v68, s22, v59
	v_and_or_b32 v58, v69, s22, v58
	v_ashrrev_i32_e32 v67, 31, v66
	global_store_dwordx4 v[96:97], v[58:61], off offset:1024
	s_and_b64 vcc, exec, s[0:1]
	s_nop 0
	v_lshlrev_b64 v[58:59], 11, v[66:67]
	v_lshl_add_u64 v[68:69], s[6:7], 0, v[58:59]
	s_cbranch_vccnz .LBB0_791
	v_lshl_add_u64 v[58:59], v[68:69], 0, v[74:75]
	v_mov_b64_e32 v[62:63], v[162:163]
	v_mov_b64_e32 v[64:65], v[164:165]
	s_cbranch_execz .LBB0_792

.LBB0_790:
	v_mov_b32_e32 v95, v75
	v_lshl_add_u64 v[58:59], v[68:69], 0, v[94:95]
	v_mov_b64_e32 v[58:59], v[166:167]
	v_mov_b64_e32 v[60:61], v[168:169]
	s_cbranch_execz .LBB0_794
	s_branch .LBB0_795

.LBB0_795:
	v_lshlrev_b32_e32 v68, 16, v54
	v_mul_f32_e32 v69, 0xbfb8aa3b, v68
	v_and_b32_e32 v54, 0xffff0000, v54
	v_exp_f32_e32 v70, v69
	v_lshlrev_b32_e32 v69, 16, v55
	v_mul_f32_e32 v71, 0xbfb8aa3b, v54
	v_exp_f32_e32 v71, v71
	v_mul_f32_e32 v72, 0xbfb8aa3b, v69
	v_exp_f32_e32 v73, v72
	v_and_b32_e32 v55, 0xffff0000, v55
	v_add_f32_e32 v71, 1.0, v71
	v_add_f32_e32 v70, 1.0, v70
	v_rcp_f32_e32 v72, v71
	v_add_f32_e32 v71, 1.0, v73
	v_mul_f32_e32 v73, 0xbfb8aa3b, v55
	v_rcp_f32_e32 v70, v70
	v_rcp_f32_e32 v71, v71
	v_exp_f32_e32 v73, v73
	s_waitcnt vmcnt(0) lgkmcnt(0)
	v_lshlrev_b32_e32 v97, 16, v63
	v_lshlrev_b32_e32 v96, 16, v62
	v_pk_mul_f32 v[68:69], v[70:71], v[68:69]
	v_add_f32_e32 v70, 1.0, v73
	v_rcp_f32_e32 v73, v70
	v_and_b32_e32 v63, 0xffff0000, v63
	v_and_b32_e32 v62, 0xffff0000, v62
	v_pk_mul_f32 v[68:69], v[68:69], v[96:97]
	v_pk_mul_f32 v[54:55], v[72:73], v[54:55]
	v_lshlrev_b32_e32 v99, 16, v65
	v_pk_mul_f32 v[54:55], v[54:55], v[62:63]
	v_lshlrev_b32_e32 v62, 16, v56
	v_mul_f32_e32 v63, 0xbfb8aa3b, v62
	v_and_b32_e32 v56, 0xffff0000, v56
	v_exp_f32_e32 v72, v63
	v_lshlrev_b32_e32 v63, 16, v57
	v_mul_f32_e32 v73, 0xbfb8aa3b, v56
	v_exp_f32_e32 v73, v73
	v_mul_f32_e32 v95, 0xbfb8aa3b, v63
	v_exp_f32_e32 v95, v95
	v_and_b32_e32 v57, 0xffff0000, v57
	v_add_f32_e32 v73, 1.0, v73
	v_add_f32_e32 v72, 1.0, v72
	v_rcp_f32_e32 v96, v73
	v_add_f32_e32 v73, 1.0, v95
	v_mul_f32_e32 v95, 0xbfb8aa3b, v57
	v_rcp_f32_e32 v72, v72
	v_rcp_f32_e32 v73, v73
	v_exp_f32_e32 v95, v95
	v_lshlrev_b32_e32 v98, 16, v64
	v_and_b32_e32 v65, 0xffff0000, v65
	v_pk_mul_f32 v[62:63], v[72:73], v[62:63]
	v_add_f32_e32 v72, 1.0, v95
	v_rcp_f32_e32 v97, v72
	v_and_b32_e32 v64, 0xffff0000, v64
	v_pk_mul_f32 v[62:63], v[62:63], v[98:99]
	v_lshlrev_b32_e32 v141, 16, v59
	v_pk_mul_f32 v[56:57], v[96:97], v[56:57]
	v_lshlrev_b32_e32 v140, 16, v58
	v_pk_mul_f32 v[56:57], v[56:57], v[64:65]
	v_lshlrev_b32_e32 v64, 16, v50
	v_mul_f32_e32 v65, 0xbfb8aa3b, v64
	v_exp_f32_e32 v95, v65
	v_and_b32_e32 v50, 0xffff0000, v50
	v_lshlrev_b32_e32 v65, 16, v51
	v_mul_f32_e32 v97, 0xbfb8aa3b, v65
	v_add_f32_e32 v95, 1.0, v95
	v_rcp_f32_e32 v96, v95
	v_mul_f32_e32 v95, 0xbfb8aa3b, v50
	v_exp_f32_e32 v95, v95
	v_exp_f32_e32 v97, v97
	v_and_b32_e32 v51, 0xffff0000, v51
	v_and_b32_e32 v59, 0xffff0000, v59
	v_add_f32_e32 v95, 1.0, v95
	v_rcp_f32_e32 v98, v95
	v_add_f32_e32 v95, 1.0, v97
	v_rcp_f32_e32 v97, v95
	v_mul_f32_e32 v95, 0xbfb8aa3b, v51
	v_exp_f32_e32 v95, v95
	v_and_b32_e32 v58, 0xffff0000, v58
	v_pk_mul_f32 v[64:65], v[96:97], v[64:65]
	v_pk_mul_f32 v[70:71], v[54:55], v[54:55]
	v_add_f32_e32 v95, 1.0, v95
	v_rcp_f32_e32 v99, v95
	v_pk_mul_f32 v[64:65], v[64:65], v[140:141]
	v_lshlrev_b32_e32 v143, 16, v61
	v_lshlrev_b32_e32 v142, 16, v60
	v_pk_mul_f32 v[50:51], v[98:99], v[50:51]
	v_pk_fma_f32 v[70:71], v[68:69], v[68:69], v[70:71]
	v_pk_mul_f32 v[58:59], v[50:51], v[58:59]
	v_lshlrev_b32_e32 v50, 16, v52
	v_mul_f32_e32 v51, 0xbfb8aa3b, v50
	v_exp_f32_e32 v95, v51
	v_and_b32_e32 v52, 0xffff0000, v52
	v_lshlrev_b32_e32 v51, 16, v53
	v_mul_f32_e32 v99, 0xbfb8aa3b, v51
	v_add_f32_e32 v95, 1.0, v95
	v_rcp_f32_e32 v98, v95
	v_mul_f32_e32 v95, 0xbfb8aa3b, v52
	v_exp_f32_e32 v95, v95
	v_exp_f32_e32 v99, v99
	v_and_b32_e32 v53, 0xffff0000, v53
	v_pk_mul_f32 v[72:73], v[56:57], v[56:57]
	v_add_f32_e32 v95, 1.0, v95
	v_rcp_f32_e32 v140, v95
	v_add_f32_e32 v95, 1.0, v99
	v_rcp_f32_e32 v99, v95
	v_mul_f32_e32 v95, 0xbfb8aa3b, v53
	v_exp_f32_e32 v95, v95
	v_pk_fma_f32 v[72:73], v[62:63], v[62:63], v[72:73]
	v_pk_mul_f32 v[50:51], v[98:99], v[50:51]
	v_pk_mul_f32 v[96:97], v[58:59], v[58:59]
	v_add_f32_e32 v95, 1.0, v95
	v_rcp_f32_e32 v141, v95
	v_pk_mul_f32 v[98:99], v[50:51], v[142:143]
	v_and_b32_e32 v51, 0xffff0000, v61
	v_and_b32_e32 v50, 0xffff0000, v60
	v_pk_mul_f32 v[52:53], v[140:141], v[52:53]
	v_pk_fma_f32 v[96:97], v[64:65], v[64:65], v[96:97]
	v_pk_mul_f32 v[60:61], v[52:53], v[50:51]
	v_add_f32_e32 v52, v70, v71
	v_add_f32_e32 v52, v72, v52
	v_add_f32_e32 v52, v73, v52
	v_pk_mul_f32 v[50:51], v[60:61], v[60:61]
	v_add_f32_e32 v52, v52, v96
	v_pk_fma_f32 v[50:51], v[98:99], v[98:99], v[50:51]
	v_add_f32_e32 v52, v97, v52
	v_add_f32_e32 v50, v50, v52
	v_add_f32_e32 v50, v51, v50
	ds_bpermute_b32 v51, v93, v50
	s_mov_b64 s[16:17], -1
	s_waitcnt lgkmcnt(0)
	v_add_f32_e32 v50, v50, v51
	ds_bpermute_b32 v51, v100, v50
	s_waitcnt lgkmcnt(0)
	v_add_f32_e32 v50, v50, v51
	ds_bpermute_b32 v51, v101, v50
	s_waitcnt lgkmcnt(0)
	v_add_f32_e32 v50, v50, v51
	ds_bpermute_b32 v51, v102, v50
	s_waitcnt lgkmcnt(0)
	v_add_f32_e32 v50, v50, v51
	ds_bpermute_b32 v51, v103, v50
	s_waitcnt lgkmcnt(0)
	v_add_f32_e32 v50, v50, v51
	ds_bpermute_b32 v51, v104, v50
	s_waitcnt lgkmcnt(0)
	v_add_f32_e32 v50, v50, v51
	v_fmamk_f32 v50, v50, 0x3a800000, v138
	v_mul_f32_e32 v51, 0x4b800000, v50
	v_cmp_gt_f32_e32 vcc, s23, v50
	s_nop 1
	v_cndmask_b32_e32 v50, v50, v51, vcc
	v_rsq_f32_e32 v52, v50
	v_lshlrev_b64 v[50:51], 12, v[66:67]
	v_lshl_add_u64 v[50:51], s[10:11], 0, v[50:51]
	v_lshl_add_u64 v[66:67], v[50:51], 0, v[74:75]
	v_mul_f32_e32 v50, 0x45800000, v52
	v_cndmask_b32_e32 v70, v52, v50, vcc
	v_pk_mul_f32 v[52:53], v[54:55], v[70:71] op_sel_hi:[1,0]
	v_pk_mul_f32 v[56:57], v[56:57], v[70:71] op_sel_hi:[1,0]
	v_pk_mul_f32 v[50:51], v[68:69], v[70:71] op_sel_hi:[1,0]
	v_pk_mul_f32 v[54:55], v[62:63], v[70:71] op_sel_hi:[1,0]
	v_bfe_u32 v62, v57, 16, 1
	v_bfe_u32 v63, v56, 16, 1
	v_bfe_u32 v68, v53, 16, 1
	v_bfe_u32 v69, v52, 16, 1
	v_add3_u32 v69, v52, v69, s24
	v_add3_u32 v68, v53, v68, s24
	v_add3_u32 v52, v56, v63, s24
	v_add3_u32 v53, v57, v62, s24
	v_bfe_u32 v56, v50, 16, 1
	v_bfe_u32 v57, v51, 16, 1
	v_bfe_u32 v62, v54, 16, 1
	v_bfe_u32 v63, v55, 16, 1
	v_add3_u32 v55, v55, v63, s24
	v_add3_u32 v54, v54, v62, s24
	v_add3_u32 v51, v51, v57, s24
	v_add3_u32 v50, v50, v56, s24
	v_lshrrev_b32_e32 v50, 16, v50
	v_lshrrev_b32_e32 v51, 16, v51
	v_lshrrev_b32_e32 v54, 16, v54
	v_lshrrev_b32_e32 v55, 16, v55
	v_and_or_b32 v53, v53, s22, v55
	v_and_or_b32 v52, v52, s22, v54
	v_and_or_b32 v51, v68, s22, v51
	v_and_or_b32 v50, v69, s22, v50
	global_store_dwordx4 v[66:67], v[50:53], off
	v_pk_mul_f32 v[56:57], v[60:61], v[70:71] op_sel_hi:[1,0]
	v_pk_mul_f32 v[54:55], v[98:99], v[70:71] op_sel_hi:[1,0]
	v_pk_mul_f32 v[52:53], v[58:59], v[70:71] op_sel_hi:[1,0]
	v_pk_mul_f32 v[50:51], v[64:65], v[70:71] op_sel_hi:[1,0]
	v_bfe_u32 v58, v57, 16, 1
	v_bfe_u32 v59, v56, 16, 1
	v_bfe_u32 v60, v53, 16, 1
	v_bfe_u32 v61, v52, 16, 1
	v_add3_u32 v61, v52, v61, s24
	v_add3_u32 v60, v53, v60, s24
	v_add3_u32 v52, v56, v59, s24
	v_add3_u32 v53, v57, v58, s24
	v_bfe_u32 v56, v50, 16, 1
	v_bfe_u32 v57, v51, 16, 1
	v_bfe_u32 v58, v54, 16, 1
	v_bfe_u32 v59, v55, 16, 1
	v_add3_u32 v55, v55, v59, s24
	v_add3_u32 v54, v54, v58, s24
	v_add3_u32 v51, v51, v57, s24
	v_add3_u32 v50, v50, v56, s24
	v_lshrrev_b32_e32 v50, 16, v50
	v_lshrrev_b32_e32 v51, 16, v51
	v_lshrrev_b32_e32 v54, 16, v54
	v_lshrrev_b32_e32 v55, 16, v55
	v_add_u32_e32 v58, s8, v126
	v_and_or_b32 v53, v53, s22, v55
	v_and_or_b32 v52, v52, s22, v54
	v_and_or_b32 v51, v60, s22, v51
	v_and_or_b32 v50, v61, s22, v50
	v_ashrrev_i32_e32 v59, 31, v58
	global_store_dwordx4 v[66:67], v[50:53], off offset:1024
	s_and_b64 vcc, exec, s[0:1]
	s_nop 0
	v_lshlrev_b64 v[50:51], 11, v[58:59]
	v_lshl_add_u64 v[60:61], s[6:7], 0, v[50:51]
	s_cbranch_vccnz .LBB0_799
	v_lshl_add_u64 v[50:51], v[60:61], 0, v[74:75]
	v_mov_b64_e32 v[54:55], v[170:171]
	v_mov_b64_e32 v[56:57], v[172:173]
	s_cbranch_execz .LBB0_800

.LBB0_798:
	v_mov_b32_e32 v95, v75
	v_lshl_add_u64 v[50:51], v[60:61], 0, v[94:95]
	v_mov_b64_e32 v[50:51], v[174:175]
	v_mov_b64_e32 v[52:53], v[176:177]
	s_cbranch_execz .LBB0_802
	s_branch .LBB0_803

.LBB0_803:
	v_lshlrev_b32_e32 v60, 16, v46
	v_mul_f32_e32 v61, 0xbfb8aa3b, v60
	v_and_b32_e32 v46, 0xffff0000, v46
	v_exp_f32_e32 v62, v61
	v_lshlrev_b32_e32 v61, 16, v47
	v_mul_f32_e32 v63, 0xbfb8aa3b, v46
	v_exp_f32_e32 v63, v63
	v_mul_f32_e32 v64, 0xbfb8aa3b, v61
	v_exp_f32_e32 v65, v64
	v_and_b32_e32 v47, 0xffff0000, v47
	v_add_f32_e32 v63, 1.0, v63
	v_add_f32_e32 v62, 1.0, v62
	v_rcp_f32_e32 v64, v63
	v_add_f32_e32 v63, 1.0, v65
	v_mul_f32_e32 v65, 0xbfb8aa3b, v47
	v_rcp_f32_e32 v62, v62
	v_rcp_f32_e32 v63, v63
	v_exp_f32_e32 v65, v65
	s_waitcnt vmcnt(0) lgkmcnt(0)
	v_lshlrev_b32_e32 v67, 16, v55
	v_lshlrev_b32_e32 v66, 16, v54
	v_pk_mul_f32 v[60:61], v[62:63], v[60:61]
	v_add_f32_e32 v62, 1.0, v65
	v_rcp_f32_e32 v65, v62
	v_and_b32_e32 v55, 0xffff0000, v55
	v_and_b32_e32 v54, 0xffff0000, v54
	v_pk_mul_f32 v[60:61], v[60:61], v[66:67]
	v_pk_mul_f32 v[46:47], v[64:65], v[46:47]
	v_lshlrev_b32_e32 v69, 16, v57
	v_pk_mul_f32 v[46:47], v[46:47], v[54:55]
	v_lshlrev_b32_e32 v54, 16, v48
	v_mul_f32_e32 v55, 0xbfb8aa3b, v54
	v_and_b32_e32 v48, 0xffff0000, v48
	v_exp_f32_e32 v64, v55
	v_lshlrev_b32_e32 v55, 16, v49
	v_mul_f32_e32 v65, 0xbfb8aa3b, v48
	v_exp_f32_e32 v65, v65
	v_mul_f32_e32 v66, 0xbfb8aa3b, v55
	v_exp_f32_e32 v67, v66
	v_and_b32_e32 v49, 0xffff0000, v49
	v_add_f32_e32 v65, 1.0, v65
	v_add_f32_e32 v64, 1.0, v64
	v_rcp_f32_e32 v66, v65
	v_add_f32_e32 v65, 1.0, v67
	v_mul_f32_e32 v67, 0xbfb8aa3b, v49
	v_rcp_f32_e32 v64, v64
	v_rcp_f32_e32 v65, v65
	v_exp_f32_e32 v67, v67
	v_lshlrev_b32_e32 v68, 16, v56
	v_and_b32_e32 v57, 0xffff0000, v57
	v_pk_mul_f32 v[54:55], v[64:65], v[54:55]
	v_add_f32_e32 v64, 1.0, v67
	v_rcp_f32_e32 v67, v64
	v_and_b32_e32 v56, 0xffff0000, v56
	v_pk_mul_f32 v[54:55], v[54:55], v[68:69]
	v_lshlrev_b32_e32 v71, 16, v51
	v_pk_mul_f32 v[48:49], v[66:67], v[48:49]
	v_lshlrev_b32_e32 v70, 16, v50
	v_pk_mul_f32 v[48:49], v[48:49], v[56:57]
	v_lshlrev_b32_e32 v56, 16, v42
	v_mul_f32_e32 v57, 0xbfb8aa3b, v56
	v_and_b32_e32 v42, 0xffff0000, v42
	v_exp_f32_e32 v66, v57
	v_lshlrev_b32_e32 v57, 16, v43
	v_mul_f32_e32 v67, 0xbfb8aa3b, v42
	v_exp_f32_e32 v67, v67
	v_mul_f32_e32 v68, 0xbfb8aa3b, v57
	v_exp_f32_e32 v69, v68
	v_and_b32_e32 v43, 0xffff0000, v43
	v_add_f32_e32 v67, 1.0, v67
	v_add_f32_e32 v66, 1.0, v66
	v_rcp_f32_e32 v68, v67
	v_add_f32_e32 v67, 1.0, v69
	v_mul_f32_e32 v69, 0xbfb8aa3b, v43
	v_rcp_f32_e32 v66, v66
	v_rcp_f32_e32 v67, v67
	v_exp_f32_e32 v69, v69
	v_and_b32_e32 v51, 0xffff0000, v51
	v_and_b32_e32 v50, 0xffff0000, v50
	v_pk_mul_f32 v[56:57], v[66:67], v[56:57]
	v_add_f32_e32 v66, 1.0, v69
	v_rcp_f32_e32 v69, v66
	v_pk_mul_f32 v[56:57], v[56:57], v[70:71]
	v_pk_mul_f32 v[62:63], v[46:47], v[46:47]
	v_lshlrev_b32_e32 v73, 16, v53
	v_pk_mul_f32 v[42:43], v[68:69], v[42:43]
	v_lshlrev_b32_e32 v72, 16, v52
	v_pk_mul_f32 v[50:51], v[42:43], v[50:51]
	v_lshlrev_b32_e32 v42, 16, v44
	v_mul_f32_e32 v43, 0xbfb8aa3b, v42
	v_and_b32_e32 v44, 0xffff0000, v44
	v_exp_f32_e32 v68, v43
	v_lshlrev_b32_e32 v43, 16, v45
	v_mul_f32_e32 v69, 0xbfb8aa3b, v44
	v_exp_f32_e32 v69, v69
	v_mul_f32_e32 v70, 0xbfb8aa3b, v43
	v_exp_f32_e32 v71, v70
	v_and_b32_e32 v45, 0xffff0000, v45
	v_add_f32_e32 v69, 1.0, v69
	v_add_f32_e32 v68, 1.0, v68
	v_rcp_f32_e32 v70, v69
	v_add_f32_e32 v69, 1.0, v71
	v_mul_f32_e32 v71, 0xbfb8aa3b, v45
	v_rcp_f32_e32 v68, v68
	v_rcp_f32_e32 v69, v69
	v_exp_f32_e32 v71, v71
	v_pk_fma_f32 v[62:63], v[60:61], v[60:61], v[62:63]
	v_pk_mul_f32 v[64:65], v[48:49], v[48:49]
	v_pk_mul_f32 v[42:43], v[68:69], v[42:43]
	v_add_f32_e32 v68, 1.0, v71
	v_rcp_f32_e32 v71, v68
	v_pk_mul_f32 v[68:69], v[42:43], v[72:73]
	v_and_b32_e32 v43, 0xffff0000, v53
	v_and_b32_e32 v42, 0xffff0000, v52
	v_pk_mul_f32 v[44:45], v[70:71], v[44:45]
	v_pk_fma_f32 v[64:65], v[54:55], v[54:55], v[64:65]
	v_pk_mul_f32 v[52:53], v[44:45], v[42:43]
	v_add_f32_e32 v44, v62, v63
	v_pk_mul_f32 v[66:67], v[50:51], v[50:51]
	v_add_f32_e32 v44, v64, v44
	v_pk_fma_f32 v[66:67], v[56:57], v[56:57], v[66:67]
	v_add_f32_e32 v44, v65, v44
	v_pk_mul_f32 v[42:43], v[52:53], v[52:53]
	v_add_f32_e32 v44, v44, v66
	v_pk_fma_f32 v[42:43], v[68:69], v[68:69], v[42:43]
	v_add_f32_e32 v44, v67, v44
	v_add_f32_e32 v42, v42, v44
	v_add_f32_e32 v42, v43, v42
	ds_bpermute_b32 v43, v93, v42
	s_mov_b64 s[16:17], -1
	s_waitcnt lgkmcnt(0)
	v_add_f32_e32 v42, v42, v43
	ds_bpermute_b32 v43, v100, v42
	s_waitcnt lgkmcnt(0)
	v_add_f32_e32 v42, v42, v43
	ds_bpermute_b32 v43, v101, v42
	s_waitcnt lgkmcnt(0)
	v_add_f32_e32 v42, v42, v43
	ds_bpermute_b32 v43, v102, v42
	s_waitcnt lgkmcnt(0)
	v_add_f32_e32 v42, v42, v43
	ds_bpermute_b32 v43, v103, v42
	s_waitcnt lgkmcnt(0)
	v_add_f32_e32 v42, v42, v43
	ds_bpermute_b32 v43, v104, v42
	s_waitcnt lgkmcnt(0)
	v_add_f32_e32 v42, v42, v43
	v_fmamk_f32 v42, v42, 0x3a800000, v138
	v_mul_f32_e32 v43, 0x4b800000, v42
	v_cmp_gt_f32_e32 vcc, s23, v42
	s_nop 1
	v_cndmask_b32_e32 v42, v42, v43, vcc
	v_rsq_f32_e32 v44, v42
	v_lshlrev_b64 v[42:43], 12, v[58:59]
	v_lshl_add_u64 v[42:43], s[10:11], 0, v[42:43]
	v_lshl_add_u64 v[58:59], v[42:43], 0, v[74:75]
	v_mul_f32_e32 v42, 0x45800000, v44
	v_cndmask_b32_e32 v62, v44, v42, vcc
	v_pk_mul_f32 v[44:45], v[46:47], v[62:63] op_sel_hi:[1,0]
	v_pk_mul_f32 v[48:49], v[48:49], v[62:63] op_sel_hi:[1,0]
	v_pk_mul_f32 v[42:43], v[60:61], v[62:63] op_sel_hi:[1,0]
	v_pk_mul_f32 v[46:47], v[54:55], v[62:63] op_sel_hi:[1,0]
	v_bfe_u32 v54, v49, 16, 1
	v_bfe_u32 v55, v48, 16, 1
	v_bfe_u32 v60, v45, 16, 1
	v_bfe_u32 v61, v44, 16, 1
	v_add3_u32 v61, v44, v61, s24
	v_add3_u32 v60, v45, v60, s24
	v_add3_u32 v44, v48, v55, s24
	v_add3_u32 v45, v49, v54, s24
	v_bfe_u32 v48, v42, 16, 1
	v_bfe_u32 v49, v43, 16, 1
	v_bfe_u32 v54, v46, 16, 1
	v_bfe_u32 v55, v47, 16, 1
	v_add3_u32 v47, v47, v55, s24
	v_add3_u32 v46, v46, v54, s24
	v_add3_u32 v43, v43, v49, s24
	v_add3_u32 v42, v42, v48, s24
	v_lshrrev_b32_e32 v42, 16, v42
	v_lshrrev_b32_e32 v43, 16, v43
	v_lshrrev_b32_e32 v46, 16, v46
	v_lshrrev_b32_e32 v47, 16, v47
	v_and_or_b32 v45, v45, s22, v47
	v_and_or_b32 v44, v44, s22, v46
	v_and_or_b32 v43, v60, s22, v43
	v_and_or_b32 v42, v61, s22, v42
	global_store_dwordx4 v[58:59], v[42:45], off
	v_pk_mul_f32 v[48:49], v[52:53], v[62:63] op_sel_hi:[1,0]
	v_pk_mul_f32 v[46:47], v[68:69], v[62:63] op_sel_hi:[1,0]
	v_pk_mul_f32 v[44:45], v[50:51], v[62:63] op_sel_hi:[1,0]
	v_pk_mul_f32 v[42:43], v[56:57], v[62:63] op_sel_hi:[1,0]
	v_bfe_u32 v50, v49, 16, 1
	v_bfe_u32 v51, v48, 16, 1
	v_bfe_u32 v52, v45, 16, 1
	v_bfe_u32 v53, v44, 16, 1
	v_add3_u32 v53, v44, v53, s24
	v_add3_u32 v52, v45, v52, s24
	v_add3_u32 v44, v48, v51, s24
	v_add3_u32 v45, v49, v50, s24
	v_bfe_u32 v48, v42, 16, 1
	v_bfe_u32 v49, v43, 16, 1
	v_bfe_u32 v50, v46, 16, 1
	v_bfe_u32 v51, v47, 16, 1
	v_add3_u32 v47, v47, v51, s24
	v_add3_u32 v46, v46, v50, s24
	v_add3_u32 v43, v43, v49, s24
	v_add3_u32 v42, v42, v48, s24
	v_lshrrev_b32_e32 v42, 16, v42
	v_lshrrev_b32_e32 v43, 16, v43
	v_lshrrev_b32_e32 v46, 16, v46
	v_lshrrev_b32_e32 v47, 16, v47
	v_add_u32_e32 v50, s8, v128
	v_and_or_b32 v45, v45, s22, v47
	v_and_or_b32 v44, v44, s22, v46
	v_and_or_b32 v43, v52, s22, v43
	v_and_or_b32 v42, v53, s22, v42
	v_ashrrev_i32_e32 v51, 31, v50
	global_store_dwordx4 v[58:59], v[42:45], off offset:1024
	s_and_b64 vcc, exec, s[0:1]
	s_nop 0
	v_lshlrev_b64 v[42:43], 11, v[50:51]
	v_lshl_add_u64 v[52:53], s[6:7], 0, v[42:43]
	s_cbranch_vccnz .LBB0_807
	v_lshl_add_u64 v[42:43], v[52:53], 0, v[74:75]
	v_mov_b64_e32 v[46:47], v[178:179]
	v_mov_b64_e32 v[48:49], v[180:181]
	s_cbranch_execz .LBB0_808

.LBB0_806:
	v_mov_b32_e32 v95, v75
	v_lshl_add_u64 v[42:43], v[52:53], 0, v[94:95]
	v_mov_b64_e32 v[42:43], v[182:183]
	v_mov_b64_e32 v[44:45], v[184:185]
	s_cbranch_execz .LBB0_810
	s_branch .LBB0_811

.LBB0_811:
	v_lshlrev_b32_e32 v52, 16, v38
	v_mul_f32_e32 v53, 0xbfb8aa3b, v52
	v_and_b32_e32 v38, 0xffff0000, v38
	v_exp_f32_e32 v54, v53
	v_lshlrev_b32_e32 v53, 16, v39
	v_mul_f32_e32 v55, 0xbfb8aa3b, v38
	v_exp_f32_e32 v55, v55
	v_mul_f32_e32 v56, 0xbfb8aa3b, v53
	v_exp_f32_e32 v57, v56
	v_and_b32_e32 v39, 0xffff0000, v39
	v_add_f32_e32 v55, 1.0, v55
	v_add_f32_e32 v54, 1.0, v54
	v_rcp_f32_e32 v56, v55
	v_add_f32_e32 v55, 1.0, v57
	v_mul_f32_e32 v57, 0xbfb8aa3b, v39
	v_rcp_f32_e32 v54, v54
	v_rcp_f32_e32 v55, v55
	v_exp_f32_e32 v57, v57
	s_waitcnt vmcnt(0) lgkmcnt(0)
	v_lshlrev_b32_e32 v59, 16, v47
	v_lshlrev_b32_e32 v58, 16, v46
	v_pk_mul_f32 v[52:53], v[54:55], v[52:53]
	v_add_f32_e32 v54, 1.0, v57
	v_rcp_f32_e32 v57, v54
	v_and_b32_e32 v47, 0xffff0000, v47
	v_and_b32_e32 v46, 0xffff0000, v46
	v_pk_mul_f32 v[52:53], v[52:53], v[58:59]
	v_pk_mul_f32 v[38:39], v[56:57], v[38:39]
	v_lshlrev_b32_e32 v61, 16, v49
	v_pk_mul_f32 v[38:39], v[38:39], v[46:47]
	v_lshlrev_b32_e32 v46, 16, v40
	v_mul_f32_e32 v47, 0xbfb8aa3b, v46
	v_and_b32_e32 v40, 0xffff0000, v40
	v_exp_f32_e32 v56, v47
	v_lshlrev_b32_e32 v47, 16, v41
	v_mul_f32_e32 v57, 0xbfb8aa3b, v40
	v_exp_f32_e32 v57, v57
	v_mul_f32_e32 v58, 0xbfb8aa3b, v47
	v_exp_f32_e32 v59, v58
	v_and_b32_e32 v41, 0xffff0000, v41
	v_add_f32_e32 v57, 1.0, v57
	v_add_f32_e32 v56, 1.0, v56
	v_rcp_f32_e32 v58, v57
	v_add_f32_e32 v57, 1.0, v59
	v_mul_f32_e32 v59, 0xbfb8aa3b, v41
	v_rcp_f32_e32 v56, v56
	v_rcp_f32_e32 v57, v57
	v_exp_f32_e32 v59, v59
	v_lshlrev_b32_e32 v60, 16, v48
	v_and_b32_e32 v49, 0xffff0000, v49
	v_pk_mul_f32 v[46:47], v[56:57], v[46:47]
	v_add_f32_e32 v56, 1.0, v59
	v_rcp_f32_e32 v59, v56
	v_and_b32_e32 v48, 0xffff0000, v48
	v_pk_mul_f32 v[46:47], v[46:47], v[60:61]
	v_lshlrev_b32_e32 v63, 16, v43
	v_pk_mul_f32 v[40:41], v[58:59], v[40:41]
	v_lshlrev_b32_e32 v62, 16, v42
	v_pk_mul_f32 v[40:41], v[40:41], v[48:49]
	v_lshlrev_b32_e32 v48, 16, v34
	v_mul_f32_e32 v49, 0xbfb8aa3b, v48
	v_and_b32_e32 v34, 0xffff0000, v34
	v_exp_f32_e32 v58, v49
	v_lshlrev_b32_e32 v49, 16, v35
	v_mul_f32_e32 v59, 0xbfb8aa3b, v34
	v_exp_f32_e32 v59, v59
	v_mul_f32_e32 v60, 0xbfb8aa3b, v49
	v_exp_f32_e32 v61, v60
	v_and_b32_e32 v35, 0xffff0000, v35
	v_add_f32_e32 v59, 1.0, v59
	v_add_f32_e32 v58, 1.0, v58
	v_rcp_f32_e32 v60, v59
	v_add_f32_e32 v59, 1.0, v61
	v_mul_f32_e32 v61, 0xbfb8aa3b, v35
	v_rcp_f32_e32 v58, v58
	v_rcp_f32_e32 v59, v59
	v_exp_f32_e32 v61, v61
	v_and_b32_e32 v43, 0xffff0000, v43
	v_and_b32_e32 v42, 0xffff0000, v42
	v_pk_mul_f32 v[48:49], v[58:59], v[48:49]
	v_add_f32_e32 v58, 1.0, v61
	v_rcp_f32_e32 v61, v58
	v_pk_mul_f32 v[48:49], v[48:49], v[62:63]
	v_pk_mul_f32 v[54:55], v[38:39], v[38:39]
	v_lshlrev_b32_e32 v65, 16, v45
	v_pk_mul_f32 v[34:35], v[60:61], v[34:35]
	v_lshlrev_b32_e32 v64, 16, v44
	v_pk_mul_f32 v[42:43], v[34:35], v[42:43]
	v_lshlrev_b32_e32 v34, 16, v36
	v_mul_f32_e32 v35, 0xbfb8aa3b, v34
	v_and_b32_e32 v36, 0xffff0000, v36
	v_exp_f32_e32 v60, v35
	v_lshlrev_b32_e32 v35, 16, v37
	v_mul_f32_e32 v61, 0xbfb8aa3b, v36
	v_exp_f32_e32 v61, v61
	v_mul_f32_e32 v62, 0xbfb8aa3b, v35
	v_exp_f32_e32 v63, v62
	v_and_b32_e32 v37, 0xffff0000, v37
	v_add_f32_e32 v61, 1.0, v61
	v_add_f32_e32 v60, 1.0, v60
	v_rcp_f32_e32 v62, v61
	v_add_f32_e32 v61, 1.0, v63
	v_mul_f32_e32 v63, 0xbfb8aa3b, v37
	v_rcp_f32_e32 v60, v60
	v_rcp_f32_e32 v61, v61
	v_exp_f32_e32 v63, v63
	v_pk_fma_f32 v[54:55], v[52:53], v[52:53], v[54:55]
	v_pk_mul_f32 v[56:57], v[40:41], v[40:41]
	v_pk_mul_f32 v[34:35], v[60:61], v[34:35]
	v_add_f32_e32 v60, 1.0, v63
	v_rcp_f32_e32 v63, v60
	v_pk_mul_f32 v[60:61], v[34:35], v[64:65]
	v_and_b32_e32 v35, 0xffff0000, v45
	v_and_b32_e32 v34, 0xffff0000, v44
	v_pk_mul_f32 v[36:37], v[62:63], v[36:37]
	v_pk_fma_f32 v[56:57], v[46:47], v[46:47], v[56:57]
	v_pk_mul_f32 v[44:45], v[36:37], v[34:35]
	v_add_f32_e32 v36, v54, v55
	v_pk_mul_f32 v[58:59], v[42:43], v[42:43]
	v_add_f32_e32 v36, v56, v36
	v_pk_fma_f32 v[58:59], v[48:49], v[48:49], v[58:59]
	v_add_f32_e32 v36, v57, v36
	v_pk_mul_f32 v[34:35], v[44:45], v[44:45]
	v_add_f32_e32 v36, v36, v58
	v_pk_fma_f32 v[34:35], v[60:61], v[60:61], v[34:35]
	v_add_f32_e32 v36, v59, v36
	v_add_f32_e32 v34, v34, v36
	v_add_f32_e32 v34, v35, v34
	ds_bpermute_b32 v35, v93, v34
	s_mov_b64 s[16:17], -1
	s_waitcnt lgkmcnt(0)
	v_add_f32_e32 v34, v34, v35
	ds_bpermute_b32 v35, v100, v34
	s_waitcnt lgkmcnt(0)
	v_add_f32_e32 v34, v34, v35
	ds_bpermute_b32 v35, v101, v34
	s_waitcnt lgkmcnt(0)
	v_add_f32_e32 v34, v34, v35
	ds_bpermute_b32 v35, v102, v34
	s_waitcnt lgkmcnt(0)
	v_add_f32_e32 v34, v34, v35
	ds_bpermute_b32 v35, v103, v34
	s_waitcnt lgkmcnt(0)
	v_add_f32_e32 v34, v34, v35
	ds_bpermute_b32 v35, v104, v34
	s_waitcnt lgkmcnt(0)
	v_add_f32_e32 v34, v34, v35
	v_fmamk_f32 v34, v34, 0x3a800000, v138
	v_mul_f32_e32 v35, 0x4b800000, v34
	v_cmp_gt_f32_e32 vcc, s23, v34
	s_nop 1
	v_cndmask_b32_e32 v34, v34, v35, vcc
	v_rsq_f32_e32 v36, v34
	v_lshlrev_b64 v[34:35], 12, v[50:51]
	v_lshl_add_u64 v[34:35], s[10:11], 0, v[34:35]
	v_lshl_add_u64 v[50:51], v[34:35], 0, v[74:75]
	v_mul_f32_e32 v34, 0x45800000, v36
	v_cndmask_b32_e32 v54, v36, v34, vcc
	v_pk_mul_f32 v[36:37], v[38:39], v[54:55] op_sel_hi:[1,0]
	v_pk_mul_f32 v[40:41], v[40:41], v[54:55] op_sel_hi:[1,0]
	v_pk_mul_f32 v[34:35], v[52:53], v[54:55] op_sel_hi:[1,0]
	v_pk_mul_f32 v[38:39], v[46:47], v[54:55] op_sel_hi:[1,0]
	v_bfe_u32 v46, v41, 16, 1
	v_bfe_u32 v47, v40, 16, 1
	v_bfe_u32 v52, v37, 16, 1
	v_bfe_u32 v53, v36, 16, 1
	v_add3_u32 v53, v36, v53, s24
	v_add3_u32 v52, v37, v52, s24
	v_add3_u32 v36, v40, v47, s24
	v_add3_u32 v37, v41, v46, s24
	v_bfe_u32 v40, v34, 16, 1
	v_bfe_u32 v41, v35, 16, 1
	v_bfe_u32 v46, v38, 16, 1
	v_bfe_u32 v47, v39, 16, 1
	v_add3_u32 v39, v39, v47, s24
	v_add3_u32 v38, v38, v46, s24
	v_add3_u32 v35, v35, v41, s24
	v_add3_u32 v34, v34, v40, s24
	v_lshrrev_b32_e32 v34, 16, v34
	v_lshrrev_b32_e32 v35, 16, v35
	v_lshrrev_b32_e32 v38, 16, v38
	v_lshrrev_b32_e32 v39, 16, v39
	v_and_or_b32 v37, v37, s22, v39
	v_and_or_b32 v36, v36, s22, v38
	v_and_or_b32 v35, v52, s22, v35
	v_and_or_b32 v34, v53, s22, v34
	global_store_dwordx4 v[50:51], v[34:37], off
	v_pk_mul_f32 v[40:41], v[44:45], v[54:55] op_sel_hi:[1,0]
	v_pk_mul_f32 v[38:39], v[60:61], v[54:55] op_sel_hi:[1,0]
	v_pk_mul_f32 v[36:37], v[42:43], v[54:55] op_sel_hi:[1,0]
	v_pk_mul_f32 v[34:35], v[48:49], v[54:55] op_sel_hi:[1,0]
	v_bfe_u32 v42, v41, 16, 1
	v_bfe_u32 v43, v40, 16, 1
	v_bfe_u32 v44, v37, 16, 1
	v_bfe_u32 v45, v36, 16, 1
	v_add3_u32 v45, v36, v45, s24
	v_add3_u32 v44, v37, v44, s24
	v_add3_u32 v36, v40, v43, s24
	v_add3_u32 v37, v41, v42, s24
	v_bfe_u32 v40, v34, 16, 1
	v_bfe_u32 v41, v35, 16, 1
	v_bfe_u32 v42, v38, 16, 1
	v_bfe_u32 v43, v39, 16, 1
	v_add3_u32 v39, v39, v43, s24
	v_add3_u32 v38, v38, v42, s24
	v_add3_u32 v35, v35, v41, s24
	v_add3_u32 v34, v34, v40, s24
	v_lshrrev_b32_e32 v34, 16, v34
	v_lshrrev_b32_e32 v35, 16, v35
	v_lshrrev_b32_e32 v38, 16, v38
	v_lshrrev_b32_e32 v39, 16, v39
	v_add_u32_e32 v42, s8, v130
	v_and_or_b32 v37, v37, s22, v39
	v_and_or_b32 v36, v36, s22, v38
	v_and_or_b32 v35, v44, s22, v35
	v_and_or_b32 v34, v45, s22, v34
	v_ashrrev_i32_e32 v43, 31, v42
	global_store_dwordx4 v[50:51], v[34:37], off offset:1024
	s_and_b64 vcc, exec, s[0:1]
	s_nop 0
	v_lshlrev_b64 v[34:35], 11, v[42:43]
	v_lshl_add_u64 v[44:45], s[6:7], 0, v[34:35]
	s_cbranch_vccnz .LBB0_815
	v_lshl_add_u64 v[34:35], v[44:45], 0, v[74:75]
	v_mov_b64_e32 v[38:39], v[186:187]
	v_mov_b64_e32 v[40:41], v[188:189]
	s_cbranch_execz .LBB0_816

.LBB0_814:
	v_mov_b32_e32 v95, v75
	v_lshl_add_u64 v[34:35], v[44:45], 0, v[94:95]
	v_mov_b64_e32 v[34:35], v[190:191]
	v_mov_b64_e32 v[36:37], v[192:193]
	s_cbranch_execz .LBB0_818
	s_branch .LBB0_819

.LBB0_819:
	v_lshlrev_b32_e32 v44, 16, v30
	v_mul_f32_e32 v45, 0xbfb8aa3b, v44
	v_and_b32_e32 v30, 0xffff0000, v30
	v_exp_f32_e32 v46, v45
	v_lshlrev_b32_e32 v45, 16, v31
	v_mul_f32_e32 v47, 0xbfb8aa3b, v30
	v_exp_f32_e32 v47, v47
	v_mul_f32_e32 v48, 0xbfb8aa3b, v45
	v_exp_f32_e32 v49, v48
	v_and_b32_e32 v31, 0xffff0000, v31
	v_add_f32_e32 v47, 1.0, v47
	v_add_f32_e32 v46, 1.0, v46
	v_rcp_f32_e32 v48, v47
	v_add_f32_e32 v47, 1.0, v49
	v_mul_f32_e32 v49, 0xbfb8aa3b, v31
	v_rcp_f32_e32 v46, v46
	v_rcp_f32_e32 v47, v47
	v_exp_f32_e32 v49, v49
	s_waitcnt vmcnt(0) lgkmcnt(0)
	v_lshlrev_b32_e32 v51, 16, v39
	v_lshlrev_b32_e32 v50, 16, v38
	v_pk_mul_f32 v[44:45], v[46:47], v[44:45]
	v_add_f32_e32 v46, 1.0, v49
	v_rcp_f32_e32 v49, v46
	v_and_b32_e32 v39, 0xffff0000, v39
	v_and_b32_e32 v38, 0xffff0000, v38
	v_pk_mul_f32 v[44:45], v[44:45], v[50:51]
	v_pk_mul_f32 v[30:31], v[48:49], v[30:31]
	v_lshlrev_b32_e32 v53, 16, v41
	v_pk_mul_f32 v[30:31], v[30:31], v[38:39]
	v_lshlrev_b32_e32 v38, 16, v32
	v_mul_f32_e32 v39, 0xbfb8aa3b, v38
	v_and_b32_e32 v32, 0xffff0000, v32
	v_exp_f32_e32 v48, v39
	v_lshlrev_b32_e32 v39, 16, v33
	v_mul_f32_e32 v49, 0xbfb8aa3b, v32
	v_exp_f32_e32 v49, v49
	v_mul_f32_e32 v50, 0xbfb8aa3b, v39
	v_exp_f32_e32 v51, v50
	v_and_b32_e32 v33, 0xffff0000, v33
	v_add_f32_e32 v49, 1.0, v49
	v_add_f32_e32 v48, 1.0, v48
	v_rcp_f32_e32 v50, v49
	v_add_f32_e32 v49, 1.0, v51
	v_mul_f32_e32 v51, 0xbfb8aa3b, v33
	v_rcp_f32_e32 v48, v48
	v_rcp_f32_e32 v49, v49
	v_exp_f32_e32 v51, v51
	v_lshlrev_b32_e32 v52, 16, v40
	v_and_b32_e32 v41, 0xffff0000, v41
	v_pk_mul_f32 v[38:39], v[48:49], v[38:39]
	v_add_f32_e32 v48, 1.0, v51
	v_rcp_f32_e32 v51, v48
	v_and_b32_e32 v40, 0xffff0000, v40
	v_pk_mul_f32 v[38:39], v[38:39], v[52:53]
	v_lshlrev_b32_e32 v55, 16, v35
	v_pk_mul_f32 v[32:33], v[50:51], v[32:33]
	v_lshlrev_b32_e32 v54, 16, v34
	v_pk_mul_f32 v[32:33], v[32:33], v[40:41]
	v_lshlrev_b32_e32 v40, 16, v26
	v_mul_f32_e32 v41, 0xbfb8aa3b, v40
	v_and_b32_e32 v26, 0xffff0000, v26
	v_exp_f32_e32 v50, v41
	v_lshlrev_b32_e32 v41, 16, v27
	v_mul_f32_e32 v51, 0xbfb8aa3b, v26
	v_exp_f32_e32 v51, v51
	v_mul_f32_e32 v52, 0xbfb8aa3b, v41
	v_exp_f32_e32 v53, v52
	v_and_b32_e32 v27, 0xffff0000, v27
	v_add_f32_e32 v51, 1.0, v51
	v_add_f32_e32 v50, 1.0, v50
	v_rcp_f32_e32 v52, v51
	v_add_f32_e32 v51, 1.0, v53
	v_mul_f32_e32 v53, 0xbfb8aa3b, v27
	v_rcp_f32_e32 v50, v50
	v_rcp_f32_e32 v51, v51
	v_exp_f32_e32 v53, v53
	v_and_b32_e32 v35, 0xffff0000, v35
	v_and_b32_e32 v34, 0xffff0000, v34
	v_pk_mul_f32 v[40:41], v[50:51], v[40:41]
	v_add_f32_e32 v50, 1.0, v53
	v_rcp_f32_e32 v53, v50
	v_pk_mul_f32 v[40:41], v[40:41], v[54:55]
	v_pk_mul_f32 v[46:47], v[30:31], v[30:31]
	v_lshlrev_b32_e32 v57, 16, v37
	v_pk_mul_f32 v[26:27], v[52:53], v[26:27]
	v_lshlrev_b32_e32 v56, 16, v36
	v_pk_mul_f32 v[34:35], v[26:27], v[34:35]
	v_lshlrev_b32_e32 v26, 16, v28
	v_mul_f32_e32 v27, 0xbfb8aa3b, v26
	v_and_b32_e32 v28, 0xffff0000, v28
	v_exp_f32_e32 v52, v27
	v_lshlrev_b32_e32 v27, 16, v29
	v_mul_f32_e32 v53, 0xbfb8aa3b, v28
	v_exp_f32_e32 v53, v53
	v_mul_f32_e32 v54, 0xbfb8aa3b, v27
	v_exp_f32_e32 v55, v54
	v_and_b32_e32 v29, 0xffff0000, v29
	v_add_f32_e32 v53, 1.0, v53
	v_add_f32_e32 v52, 1.0, v52
	v_rcp_f32_e32 v54, v53
	v_add_f32_e32 v53, 1.0, v55
	v_mul_f32_e32 v55, 0xbfb8aa3b, v29
	v_rcp_f32_e32 v52, v52
	v_rcp_f32_e32 v53, v53
	v_exp_f32_e32 v55, v55
	v_pk_fma_f32 v[46:47], v[44:45], v[44:45], v[46:47]
	v_pk_mul_f32 v[48:49], v[32:33], v[32:33]
	v_pk_mul_f32 v[26:27], v[52:53], v[26:27]
	v_add_f32_e32 v52, 1.0, v55
	v_rcp_f32_e32 v55, v52
	v_pk_mul_f32 v[52:53], v[26:27], v[56:57]
	v_and_b32_e32 v27, 0xffff0000, v37
	v_and_b32_e32 v26, 0xffff0000, v36
	v_pk_mul_f32 v[28:29], v[54:55], v[28:29]
	v_pk_fma_f32 v[48:49], v[38:39], v[38:39], v[48:49]
	v_pk_mul_f32 v[36:37], v[28:29], v[26:27]
	v_add_f32_e32 v28, v46, v47
	v_pk_mul_f32 v[50:51], v[34:35], v[34:35]
	v_add_f32_e32 v28, v48, v28
	v_pk_fma_f32 v[50:51], v[40:41], v[40:41], v[50:51]
	v_add_f32_e32 v28, v49, v28
	v_pk_mul_f32 v[26:27], v[36:37], v[36:37]
	v_add_f32_e32 v28, v28, v50
	v_pk_fma_f32 v[26:27], v[52:53], v[52:53], v[26:27]
	v_add_f32_e32 v28, v51, v28
	v_add_f32_e32 v26, v26, v28
	v_add_f32_e32 v26, v27, v26
	ds_bpermute_b32 v27, v93, v26
	s_mov_b64 s[16:17], -1
	s_waitcnt lgkmcnt(0)
	v_add_f32_e32 v26, v26, v27
	ds_bpermute_b32 v27, v100, v26
	s_waitcnt lgkmcnt(0)
	v_add_f32_e32 v26, v26, v27
	ds_bpermute_b32 v27, v101, v26
	s_waitcnt lgkmcnt(0)
	v_add_f32_e32 v26, v26, v27
	ds_bpermute_b32 v27, v102, v26
	s_waitcnt lgkmcnt(0)
	v_add_f32_e32 v26, v26, v27
	ds_bpermute_b32 v27, v103, v26
	s_waitcnt lgkmcnt(0)
	v_add_f32_e32 v26, v26, v27
	ds_bpermute_b32 v27, v104, v26
	s_waitcnt lgkmcnt(0)
	v_add_f32_e32 v26, v26, v27
	v_fmamk_f32 v26, v26, 0x3a800000, v138
	v_mul_f32_e32 v27, 0x4b800000, v26
	v_cmp_gt_f32_e32 vcc, s23, v26
	s_nop 1
	v_cndmask_b32_e32 v26, v26, v27, vcc
	v_rsq_f32_e32 v28, v26
	v_lshlrev_b64 v[26:27], 12, v[42:43]
	v_lshl_add_u64 v[26:27], s[10:11], 0, v[26:27]
	v_lshl_add_u64 v[42:43], v[26:27], 0, v[74:75]
	v_mul_f32_e32 v26, 0x45800000, v28
	v_cndmask_b32_e32 v46, v28, v26, vcc
	v_pk_mul_f32 v[28:29], v[30:31], v[46:47] op_sel_hi:[1,0]
	v_pk_mul_f32 v[32:33], v[32:33], v[46:47] op_sel_hi:[1,0]
	v_pk_mul_f32 v[26:27], v[44:45], v[46:47] op_sel_hi:[1,0]
	v_pk_mul_f32 v[30:31], v[38:39], v[46:47] op_sel_hi:[1,0]
	v_bfe_u32 v38, v33, 16, 1
	v_bfe_u32 v39, v32, 16, 1
	v_bfe_u32 v44, v29, 16, 1
	v_bfe_u32 v45, v28, 16, 1
	v_add3_u32 v45, v28, v45, s24
	v_add3_u32 v44, v29, v44, s24
	v_add3_u32 v28, v32, v39, s24
	v_add3_u32 v29, v33, v38, s24
	v_bfe_u32 v32, v26, 16, 1
	v_bfe_u32 v33, v27, 16, 1
	v_bfe_u32 v38, v30, 16, 1
	v_bfe_u32 v39, v31, 16, 1
	v_add3_u32 v31, v31, v39, s24
	v_add3_u32 v30, v30, v38, s24
	v_add3_u32 v27, v27, v33, s24
	v_add3_u32 v26, v26, v32, s24
	v_lshrrev_b32_e32 v26, 16, v26
	v_lshrrev_b32_e32 v27, 16, v27
	v_lshrrev_b32_e32 v30, 16, v30
	v_lshrrev_b32_e32 v31, 16, v31
	v_and_or_b32 v29, v29, s22, v31
	v_and_or_b32 v28, v28, s22, v30
	v_and_or_b32 v27, v44, s22, v27
	v_and_or_b32 v26, v45, s22, v26
	global_store_dwordx4 v[42:43], v[26:29], off
	v_pk_mul_f32 v[32:33], v[36:37], v[46:47] op_sel_hi:[1,0]
	v_pk_mul_f32 v[30:31], v[52:53], v[46:47] op_sel_hi:[1,0]
	v_pk_mul_f32 v[28:29], v[34:35], v[46:47] op_sel_hi:[1,0]
	v_pk_mul_f32 v[26:27], v[40:41], v[46:47] op_sel_hi:[1,0]
	v_bfe_u32 v34, v33, 16, 1
	v_bfe_u32 v35, v32, 16, 1
	v_bfe_u32 v36, v29, 16, 1
	v_bfe_u32 v37, v28, 16, 1
	v_add3_u32 v37, v28, v37, s24
	v_add3_u32 v36, v29, v36, s24
	v_add3_u32 v28, v32, v35, s24
	v_add3_u32 v29, v33, v34, s24
	v_bfe_u32 v32, v26, 16, 1
	v_bfe_u32 v33, v27, 16, 1
	v_bfe_u32 v34, v30, 16, 1
	v_bfe_u32 v35, v31, 16, 1
	v_add3_u32 v31, v31, v35, s24
	v_add3_u32 v30, v30, v34, s24
	v_add3_u32 v27, v27, v33, s24
	v_add3_u32 v26, v26, v32, s24
	v_lshrrev_b32_e32 v26, 16, v26
	v_lshrrev_b32_e32 v27, 16, v27
	v_lshrrev_b32_e32 v30, 16, v30
	v_lshrrev_b32_e32 v31, 16, v31
	v_add_u32_e32 v34, s8, v132
	v_and_or_b32 v29, v29, s22, v31
	v_and_or_b32 v28, v28, s22, v30
	v_and_or_b32 v27, v36, s22, v27
	v_and_or_b32 v26, v37, s22, v26
	v_ashrrev_i32_e32 v35, 31, v34
	global_store_dwordx4 v[42:43], v[26:29], off offset:1024
	s_and_b64 vcc, exec, s[0:1]
	s_nop 0
	v_lshlrev_b64 v[26:27], 11, v[34:35]
	v_lshl_add_u64 v[36:37], s[6:7], 0, v[26:27]
	s_cbranch_vccnz .LBB0_823
	v_lshl_add_u64 v[26:27], v[36:37], 0, v[74:75]
	v_mov_b64_e32 v[30:31], v[194:195]
	v_mov_b64_e32 v[32:33], v[196:197]
	s_cbranch_execz .LBB0_824

.LBB0_822:
	v_mov_b32_e32 v95, v75
	v_lshl_add_u64 v[26:27], v[36:37], 0, v[94:95]
	v_mov_b64_e32 v[26:27], v[202:203]
	v_mov_b64_e32 v[28:29], v[204:205]
	s_cbranch_execz .LBB0_826
	s_branch .LBB0_827

.LBB0_827:
	v_lshlrev_b32_e32 v36, 16, v22
	v_mul_f32_e32 v37, 0xbfb8aa3b, v36
	v_and_b32_e32 v22, 0xffff0000, v22
	v_exp_f32_e32 v38, v37
	v_lshlrev_b32_e32 v37, 16, v23
	v_mul_f32_e32 v39, 0xbfb8aa3b, v22
	v_exp_f32_e32 v39, v39
	v_mul_f32_e32 v40, 0xbfb8aa3b, v37
	v_exp_f32_e32 v41, v40
	v_and_b32_e32 v23, 0xffff0000, v23
	v_add_f32_e32 v39, 1.0, v39
	v_add_f32_e32 v38, 1.0, v38
	v_rcp_f32_e32 v40, v39
	v_add_f32_e32 v39, 1.0, v41
	v_mul_f32_e32 v41, 0xbfb8aa3b, v23
	v_rcp_f32_e32 v38, v38
	v_rcp_f32_e32 v39, v39
	v_exp_f32_e32 v41, v41
	s_waitcnt vmcnt(0) lgkmcnt(0)
	v_lshlrev_b32_e32 v43, 16, v31
	v_lshlrev_b32_e32 v42, 16, v30
	v_pk_mul_f32 v[36:37], v[38:39], v[36:37]
	v_add_f32_e32 v38, 1.0, v41
	v_rcp_f32_e32 v41, v38
	v_and_b32_e32 v31, 0xffff0000, v31
	v_and_b32_e32 v30, 0xffff0000, v30
	v_pk_mul_f32 v[36:37], v[36:37], v[42:43]
	v_pk_mul_f32 v[22:23], v[40:41], v[22:23]
	v_lshlrev_b32_e32 v45, 16, v33
	v_pk_mul_f32 v[22:23], v[22:23], v[30:31]
	v_lshlrev_b32_e32 v30, 16, v24
	v_mul_f32_e32 v31, 0xbfb8aa3b, v30
	v_and_b32_e32 v24, 0xffff0000, v24
	v_exp_f32_e32 v40, v31
	v_lshlrev_b32_e32 v31, 16, v25
	v_mul_f32_e32 v41, 0xbfb8aa3b, v24
	v_exp_f32_e32 v41, v41
	v_mul_f32_e32 v42, 0xbfb8aa3b, v31
	v_exp_f32_e32 v43, v42
	v_and_b32_e32 v25, 0xffff0000, v25
	v_add_f32_e32 v41, 1.0, v41
	v_add_f32_e32 v40, 1.0, v40
	v_rcp_f32_e32 v42, v41
	v_add_f32_e32 v41, 1.0, v43
	v_mul_f32_e32 v43, 0xbfb8aa3b, v25
	v_rcp_f32_e32 v40, v40
	v_rcp_f32_e32 v41, v41
	v_exp_f32_e32 v43, v43
	v_lshlrev_b32_e32 v44, 16, v32
	v_and_b32_e32 v33, 0xffff0000, v33
	v_pk_mul_f32 v[30:31], v[40:41], v[30:31]
	v_add_f32_e32 v40, 1.0, v43
	v_rcp_f32_e32 v43, v40
	v_and_b32_e32 v32, 0xffff0000, v32
	v_pk_mul_f32 v[30:31], v[30:31], v[44:45]
	v_lshlrev_b32_e32 v47, 16, v27
	v_pk_mul_f32 v[24:25], v[42:43], v[24:25]
	v_lshlrev_b32_e32 v46, 16, v26
	v_pk_mul_f32 v[24:25], v[24:25], v[32:33]
	v_lshlrev_b32_e32 v32, 16, v18
	v_mul_f32_e32 v33, 0xbfb8aa3b, v32
	v_and_b32_e32 v18, 0xffff0000, v18
	v_exp_f32_e32 v42, v33
	v_lshlrev_b32_e32 v33, 16, v19
	v_mul_f32_e32 v43, 0xbfb8aa3b, v18
	v_exp_f32_e32 v43, v43
	v_mul_f32_e32 v44, 0xbfb8aa3b, v33
	v_exp_f32_e32 v45, v44
	v_and_b32_e32 v19, 0xffff0000, v19
	v_add_f32_e32 v43, 1.0, v43
	v_add_f32_e32 v42, 1.0, v42
	v_rcp_f32_e32 v44, v43
	v_add_f32_e32 v43, 1.0, v45
	v_mul_f32_e32 v45, 0xbfb8aa3b, v19
	v_rcp_f32_e32 v42, v42
	v_rcp_f32_e32 v43, v43
	v_exp_f32_e32 v45, v45
	v_and_b32_e32 v27, 0xffff0000, v27
	v_and_b32_e32 v26, 0xffff0000, v26
	v_pk_mul_f32 v[32:33], v[42:43], v[32:33]
	v_add_f32_e32 v42, 1.0, v45
	v_rcp_f32_e32 v45, v42
	v_pk_mul_f32 v[32:33], v[32:33], v[46:47]
	v_pk_mul_f32 v[38:39], v[22:23], v[22:23]
	v_lshlrev_b32_e32 v49, 16, v29
	v_pk_mul_f32 v[18:19], v[44:45], v[18:19]
	v_lshlrev_b32_e32 v48, 16, v28
	v_pk_mul_f32 v[26:27], v[18:19], v[26:27]
	v_lshlrev_b32_e32 v18, 16, v20
	v_mul_f32_e32 v19, 0xbfb8aa3b, v18
	v_and_b32_e32 v20, 0xffff0000, v20
	v_exp_f32_e32 v44, v19
	v_lshlrev_b32_e32 v19, 16, v21
	v_mul_f32_e32 v45, 0xbfb8aa3b, v20
	v_exp_f32_e32 v45, v45
	v_mul_f32_e32 v46, 0xbfb8aa3b, v19
	v_exp_f32_e32 v47, v46
	v_and_b32_e32 v21, 0xffff0000, v21
	v_add_f32_e32 v45, 1.0, v45
	v_add_f32_e32 v44, 1.0, v44
	v_rcp_f32_e32 v46, v45
	v_add_f32_e32 v45, 1.0, v47
	v_mul_f32_e32 v47, 0xbfb8aa3b, v21
	v_rcp_f32_e32 v44, v44
	v_rcp_f32_e32 v45, v45
	v_exp_f32_e32 v47, v47
	v_pk_fma_f32 v[38:39], v[36:37], v[36:37], v[38:39]
	v_pk_mul_f32 v[40:41], v[24:25], v[24:25]
	v_pk_mul_f32 v[18:19], v[44:45], v[18:19]
	v_add_f32_e32 v44, 1.0, v47
	v_rcp_f32_e32 v47, v44
	v_pk_mul_f32 v[44:45], v[18:19], v[48:49]
	v_and_b32_e32 v19, 0xffff0000, v29
	v_and_b32_e32 v18, 0xffff0000, v28
	v_pk_mul_f32 v[20:21], v[46:47], v[20:21]
	v_pk_fma_f32 v[40:41], v[30:31], v[30:31], v[40:41]
	v_pk_mul_f32 v[28:29], v[20:21], v[18:19]
	v_add_f32_e32 v20, v38, v39
	v_pk_mul_f32 v[42:43], v[26:27], v[26:27]
	v_add_f32_e32 v20, v40, v20
	v_pk_fma_f32 v[42:43], v[32:33], v[32:33], v[42:43]
	v_add_f32_e32 v20, v41, v20
	v_pk_mul_f32 v[18:19], v[28:29], v[28:29]
	v_add_f32_e32 v20, v20, v42
	v_pk_fma_f32 v[18:19], v[44:45], v[44:45], v[18:19]
	v_add_f32_e32 v20, v43, v20
	v_add_f32_e32 v18, v18, v20
	v_add_f32_e32 v18, v19, v18
	ds_bpermute_b32 v19, v93, v18
	s_mov_b64 s[16:17], -1
	s_waitcnt lgkmcnt(0)
	v_add_f32_e32 v18, v18, v19
	ds_bpermute_b32 v19, v100, v18
	s_waitcnt lgkmcnt(0)
	v_add_f32_e32 v18, v18, v19
	ds_bpermute_b32 v19, v101, v18
	s_waitcnt lgkmcnt(0)
	v_add_f32_e32 v18, v18, v19
	ds_bpermute_b32 v19, v102, v18
	s_waitcnt lgkmcnt(0)
	v_add_f32_e32 v18, v18, v19
	ds_bpermute_b32 v19, v103, v18
	s_waitcnt lgkmcnt(0)
	v_add_f32_e32 v18, v18, v19
	ds_bpermute_b32 v19, v104, v18
	s_waitcnt lgkmcnt(0)
	v_add_f32_e32 v18, v18, v19
	v_fmamk_f32 v18, v18, 0x3a800000, v138
	v_mul_f32_e32 v19, 0x4b800000, v18
	v_cmp_gt_f32_e32 vcc, s23, v18
	s_nop 1
	v_cndmask_b32_e32 v18, v18, v19, vcc
	v_rsq_f32_e32 v20, v18
	v_lshlrev_b64 v[18:19], 12, v[34:35]
	v_lshl_add_u64 v[18:19], s[10:11], 0, v[18:19]
	v_lshl_add_u64 v[34:35], v[18:19], 0, v[74:75]
	v_mul_f32_e32 v18, 0x45800000, v20
	v_cndmask_b32_e32 v38, v20, v18, vcc
	v_pk_mul_f32 v[20:21], v[22:23], v[38:39] op_sel_hi:[1,0]
	v_pk_mul_f32 v[24:25], v[24:25], v[38:39] op_sel_hi:[1,0]
	v_pk_mul_f32 v[18:19], v[36:37], v[38:39] op_sel_hi:[1,0]
	v_pk_mul_f32 v[22:23], v[30:31], v[38:39] op_sel_hi:[1,0]
	v_bfe_u32 v30, v25, 16, 1
	v_bfe_u32 v31, v24, 16, 1
	v_bfe_u32 v36, v21, 16, 1
	v_bfe_u32 v37, v20, 16, 1
	v_add3_u32 v37, v20, v37, s24
	v_add3_u32 v36, v21, v36, s24
	v_add3_u32 v20, v24, v31, s24
	v_add3_u32 v21, v25, v30, s24
	v_bfe_u32 v24, v18, 16, 1
	v_bfe_u32 v25, v19, 16, 1
	v_bfe_u32 v30, v22, 16, 1
	v_bfe_u32 v31, v23, 16, 1
	v_add3_u32 v23, v23, v31, s24
	v_add3_u32 v22, v22, v30, s24
	v_add3_u32 v19, v19, v25, s24
	v_add3_u32 v18, v18, v24, s24
	v_lshrrev_b32_e32 v18, 16, v18
	v_lshrrev_b32_e32 v19, 16, v19
	v_lshrrev_b32_e32 v22, 16, v22
	v_lshrrev_b32_e32 v23, 16, v23
	v_and_or_b32 v21, v21, s22, v23
	v_and_or_b32 v20, v20, s22, v22
	v_and_or_b32 v19, v36, s22, v19
	v_and_or_b32 v18, v37, s22, v18
	global_store_dwordx4 v[34:35], v[18:21], off
	v_pk_mul_f32 v[24:25], v[28:29], v[38:39] op_sel_hi:[1,0]
	v_pk_mul_f32 v[22:23], v[44:45], v[38:39] op_sel_hi:[1,0]
	v_pk_mul_f32 v[20:21], v[26:27], v[38:39] op_sel_hi:[1,0]
	v_pk_mul_f32 v[18:19], v[32:33], v[38:39] op_sel_hi:[1,0]
	v_bfe_u32 v26, v25, 16, 1
	v_bfe_u32 v27, v24, 16, 1
	v_bfe_u32 v28, v21, 16, 1
	v_bfe_u32 v29, v20, 16, 1
	v_add3_u32 v29, v20, v29, s24
	v_add3_u32 v28, v21, v28, s24
	v_add3_u32 v20, v24, v27, s24
	v_add3_u32 v21, v25, v26, s24
	v_bfe_u32 v24, v18, 16, 1
	v_bfe_u32 v25, v19, 16, 1
	v_bfe_u32 v26, v22, 16, 1
	v_bfe_u32 v27, v23, 16, 1
	v_add3_u32 v23, v23, v27, s24
	v_add3_u32 v22, v22, v26, s24
	v_add3_u32 v19, v19, v25, s24
	v_add3_u32 v18, v18, v24, s24
	v_lshrrev_b32_e32 v18, 16, v18
	v_lshrrev_b32_e32 v19, 16, v19
	v_lshrrev_b32_e32 v22, 16, v22
	v_lshrrev_b32_e32 v23, 16, v23
	v_add_u32_e32 v26, s8, v134
	v_and_or_b32 v21, v21, s22, v23
	v_and_or_b32 v20, v20, s22, v22
	v_and_or_b32 v19, v28, s22, v19
	v_and_or_b32 v18, v29, s22, v18
	v_ashrrev_i32_e32 v27, 31, v26
	global_store_dwordx4 v[34:35], v[18:21], off offset:1024
	s_and_b64 vcc, exec, s[0:1]
	s_nop 0
	v_lshlrev_b64 v[18:19], 11, v[26:27]
	v_lshl_add_u64 v[28:29], s[6:7], 0, v[18:19]
	s_cbranch_vccnz .LBB0_831
	v_lshl_add_u64 v[18:19], v[28:29], 0, v[74:75]
	v_mov_b64_e32 v[22:23], v[206:207]
	v_mov_b64_e32 v[24:25], v[208:209]
	s_cbranch_execz .LBB0_832

.LBB0_830:
	v_mov_b32_e32 v95, v75
	v_lshl_add_u64 v[18:19], v[28:29], 0, v[94:95]
	v_mov_b64_e32 v[18:19], v[210:211]
	v_mov_b64_e32 v[20:21], v[212:213]
	s_cbranch_execz .LBB0_834
	s_branch .LBB0_835

.LBB0_835:
	v_lshlrev_b32_e32 v28, 16, v14
	v_mul_f32_e32 v29, 0xbfb8aa3b, v28
	v_and_b32_e32 v14, 0xffff0000, v14
	v_exp_f32_e32 v30, v29
	v_lshlrev_b32_e32 v29, 16, v15
	v_mul_f32_e32 v31, 0xbfb8aa3b, v14
	v_exp_f32_e32 v31, v31
	v_mul_f32_e32 v32, 0xbfb8aa3b, v29
	v_exp_f32_e32 v33, v32
	v_and_b32_e32 v15, 0xffff0000, v15
	v_add_f32_e32 v31, 1.0, v31
	v_add_f32_e32 v30, 1.0, v30
	v_rcp_f32_e32 v32, v31
	v_add_f32_e32 v31, 1.0, v33
	v_mul_f32_e32 v33, 0xbfb8aa3b, v15
	v_rcp_f32_e32 v30, v30
	v_rcp_f32_e32 v31, v31
	v_exp_f32_e32 v33, v33
	s_waitcnt vmcnt(0) lgkmcnt(0)
	v_lshlrev_b32_e32 v35, 16, v23
	v_lshlrev_b32_e32 v34, 16, v22
	v_pk_mul_f32 v[28:29], v[30:31], v[28:29]
	v_add_f32_e32 v30, 1.0, v33
	v_rcp_f32_e32 v33, v30
	v_and_b32_e32 v23, 0xffff0000, v23
	v_and_b32_e32 v22, 0xffff0000, v22
	v_pk_mul_f32 v[28:29], v[28:29], v[34:35]
	v_pk_mul_f32 v[14:15], v[32:33], v[14:15]
	v_lshlrev_b32_e32 v37, 16, v25
	v_pk_mul_f32 v[14:15], v[14:15], v[22:23]
	v_lshlrev_b32_e32 v22, 16, v16
	v_mul_f32_e32 v23, 0xbfb8aa3b, v22
	v_and_b32_e32 v16, 0xffff0000, v16
	v_exp_f32_e32 v32, v23
	v_lshlrev_b32_e32 v23, 16, v17
	v_mul_f32_e32 v33, 0xbfb8aa3b, v16
	v_exp_f32_e32 v33, v33
	v_mul_f32_e32 v34, 0xbfb8aa3b, v23
	v_exp_f32_e32 v35, v34
	v_and_b32_e32 v17, 0xffff0000, v17
	v_add_f32_e32 v33, 1.0, v33
	v_add_f32_e32 v32, 1.0, v32
	v_rcp_f32_e32 v34, v33
	v_add_f32_e32 v33, 1.0, v35
	v_mul_f32_e32 v35, 0xbfb8aa3b, v17
	v_rcp_f32_e32 v32, v32
	v_rcp_f32_e32 v33, v33
	v_exp_f32_e32 v35, v35
	v_lshlrev_b32_e32 v36, 16, v24
	v_and_b32_e32 v25, 0xffff0000, v25
	v_pk_mul_f32 v[22:23], v[32:33], v[22:23]
	v_add_f32_e32 v32, 1.0, v35
	v_rcp_f32_e32 v35, v32
	v_and_b32_e32 v24, 0xffff0000, v24
	v_pk_mul_f32 v[22:23], v[22:23], v[36:37]
	v_lshlrev_b32_e32 v39, 16, v19
	v_pk_mul_f32 v[16:17], v[34:35], v[16:17]
	v_lshlrev_b32_e32 v38, 16, v18
	v_pk_mul_f32 v[16:17], v[16:17], v[24:25]
	v_lshlrev_b32_e32 v24, 16, v10
	v_mul_f32_e32 v25, 0xbfb8aa3b, v24
	v_and_b32_e32 v10, 0xffff0000, v10
	v_exp_f32_e32 v34, v25
	v_lshlrev_b32_e32 v25, 16, v11
	v_mul_f32_e32 v35, 0xbfb8aa3b, v10
	v_exp_f32_e32 v35, v35
	v_mul_f32_e32 v36, 0xbfb8aa3b, v25
	v_exp_f32_e32 v37, v36
	v_and_b32_e32 v11, 0xffff0000, v11
	v_add_f32_e32 v35, 1.0, v35
	v_add_f32_e32 v34, 1.0, v34
	v_rcp_f32_e32 v36, v35
	v_add_f32_e32 v35, 1.0, v37
	v_mul_f32_e32 v37, 0xbfb8aa3b, v11
	v_rcp_f32_e32 v34, v34
	v_rcp_f32_e32 v35, v35
	v_exp_f32_e32 v37, v37
	v_and_b32_e32 v19, 0xffff0000, v19
	v_and_b32_e32 v18, 0xffff0000, v18
	v_pk_mul_f32 v[24:25], v[34:35], v[24:25]
	v_add_f32_e32 v34, 1.0, v37
	v_rcp_f32_e32 v37, v34
	v_pk_mul_f32 v[24:25], v[24:25], v[38:39]
	v_pk_mul_f32 v[30:31], v[14:15], v[14:15]
	v_lshlrev_b32_e32 v41, 16, v21
	v_pk_mul_f32 v[10:11], v[36:37], v[10:11]
	v_lshlrev_b32_e32 v40, 16, v20
	v_pk_mul_f32 v[18:19], v[10:11], v[18:19]
	v_lshlrev_b32_e32 v10, 16, v12
	v_mul_f32_e32 v11, 0xbfb8aa3b, v10
	v_and_b32_e32 v12, 0xffff0000, v12
	v_exp_f32_e32 v36, v11
	v_lshlrev_b32_e32 v11, 16, v13
	v_mul_f32_e32 v37, 0xbfb8aa3b, v12
	v_exp_f32_e32 v37, v37
	v_mul_f32_e32 v38, 0xbfb8aa3b, v11
	v_exp_f32_e32 v39, v38
	v_and_b32_e32 v13, 0xffff0000, v13
	v_add_f32_e32 v37, 1.0, v37
	v_add_f32_e32 v36, 1.0, v36
	v_rcp_f32_e32 v38, v37
	v_add_f32_e32 v37, 1.0, v39
	v_mul_f32_e32 v39, 0xbfb8aa3b, v13
	v_rcp_f32_e32 v36, v36
	v_rcp_f32_e32 v37, v37
	v_exp_f32_e32 v39, v39
	v_pk_fma_f32 v[30:31], v[28:29], v[28:29], v[30:31]
	v_pk_mul_f32 v[32:33], v[16:17], v[16:17]
	v_pk_mul_f32 v[10:11], v[36:37], v[10:11]
	v_add_f32_e32 v36, 1.0, v39
	v_rcp_f32_e32 v39, v36
	v_pk_mul_f32 v[36:37], v[10:11], v[40:41]
	v_and_b32_e32 v11, 0xffff0000, v21
	v_and_b32_e32 v10, 0xffff0000, v20
	v_pk_mul_f32 v[12:13], v[38:39], v[12:13]
	v_pk_fma_f32 v[32:33], v[22:23], v[22:23], v[32:33]
	v_pk_mul_f32 v[20:21], v[12:13], v[10:11]
	v_add_f32_e32 v12, v30, v31
	v_pk_mul_f32 v[34:35], v[18:19], v[18:19]
	v_add_f32_e32 v12, v32, v12
	v_pk_fma_f32 v[34:35], v[24:25], v[24:25], v[34:35]
	v_add_f32_e32 v12, v33, v12
	v_pk_mul_f32 v[10:11], v[20:21], v[20:21]
	v_add_f32_e32 v12, v12, v34
	v_pk_fma_f32 v[10:11], v[36:37], v[36:37], v[10:11]
	v_add_f32_e32 v12, v35, v12
	v_add_f32_e32 v10, v10, v12
	v_add_f32_e32 v10, v11, v10
	ds_bpermute_b32 v11, v93, v10
	s_waitcnt lgkmcnt(0)
	v_add_f32_e32 v10, v10, v11
	ds_bpermute_b32 v11, v100, v10
	s_waitcnt lgkmcnt(0)
	v_add_f32_e32 v10, v10, v11
	ds_bpermute_b32 v11, v101, v10
	s_waitcnt lgkmcnt(0)
	v_add_f32_e32 v10, v10, v11
	ds_bpermute_b32 v11, v102, v10
	s_waitcnt lgkmcnt(0)
	v_add_f32_e32 v10, v10, v11
	ds_bpermute_b32 v11, v103, v10
	s_waitcnt lgkmcnt(0)
	v_add_f32_e32 v10, v10, v11
	ds_bpermute_b32 v11, v104, v10
	s_waitcnt lgkmcnt(0)
	v_add_f32_e32 v10, v10, v11
	v_fmamk_f32 v10, v10, 0x3a800000, v138
	v_mul_f32_e32 v11, 0x4b800000, v10
	v_cmp_gt_f32_e32 vcc, s23, v10
	s_nop 1
	v_cndmask_b32_e32 v10, v10, v11, vcc
	v_rsq_f32_e32 v12, v10
	v_lshlrev_b64 v[10:11], 12, v[26:27]
	v_lshl_add_u64 v[10:11], s[10:11], 0, v[10:11]
	v_lshl_add_u64 v[26:27], v[10:11], 0, v[74:75]
	v_mul_f32_e32 v10, 0x45800000, v12
	v_cndmask_b32_e32 v30, v12, v10, vcc
	v_pk_mul_f32 v[12:13], v[14:15], v[30:31] op_sel_hi:[1,0]
	v_pk_mul_f32 v[16:17], v[16:17], v[30:31] op_sel_hi:[1,0]
	v_pk_mul_f32 v[10:11], v[28:29], v[30:31] op_sel_hi:[1,0]
	v_pk_mul_f32 v[14:15], v[22:23], v[30:31] op_sel_hi:[1,0]
	v_bfe_u32 v22, v17, 16, 1
	v_bfe_u32 v23, v16, 16, 1
	v_bfe_u32 v28, v13, 16, 1
	v_bfe_u32 v29, v12, 16, 1
	v_add3_u32 v29, v12, v29, s24
	v_add3_u32 v28, v13, v28, s24
	v_add3_u32 v12, v16, v23, s24
	v_add3_u32 v13, v17, v22, s24
	v_bfe_u32 v16, v10, 16, 1
	v_bfe_u32 v17, v11, 16, 1
	v_bfe_u32 v22, v14, 16, 1
	v_bfe_u32 v23, v15, 16, 1
	v_add3_u32 v15, v15, v23, s24
	v_add3_u32 v14, v14, v22, s24
	v_add3_u32 v11, v11, v17, s24
	v_add3_u32 v10, v10, v16, s24
	v_lshrrev_b32_e32 v10, 16, v10
	v_lshrrev_b32_e32 v11, 16, v11
	v_lshrrev_b32_e32 v14, 16, v14
	v_lshrrev_b32_e32 v15, 16, v15
	v_and_or_b32 v13, v13, s22, v15
	v_and_or_b32 v12, v12, s22, v14
	v_and_or_b32 v11, v28, s22, v11
	v_and_or_b32 v10, v29, s22, v10
	global_store_dwordx4 v[26:27], v[10:13], off
	v_pk_mul_f32 v[16:17], v[20:21], v[30:31] op_sel_hi:[1,0]
	v_pk_mul_f32 v[14:15], v[36:37], v[30:31] op_sel_hi:[1,0]
	v_pk_mul_f32 v[12:13], v[18:19], v[30:31] op_sel_hi:[1,0]
	v_pk_mul_f32 v[10:11], v[24:25], v[30:31] op_sel_hi:[1,0]
	v_bfe_u32 v18, v17, 16, 1
	v_bfe_u32 v19, v16, 16, 1
	v_bfe_u32 v20, v13, 16, 1
	v_bfe_u32 v21, v12, 16, 1
	v_add3_u32 v21, v12, v21, s24
	v_add3_u32 v20, v13, v20, s24
	v_add3_u32 v12, v16, v19, s24
	v_add3_u32 v13, v17, v18, s24
	v_bfe_u32 v16, v10, 16, 1
	v_bfe_u32 v17, v11, 16, 1
	v_bfe_u32 v18, v14, 16, 1
	v_bfe_u32 v19, v15, 16, 1
	v_add3_u32 v15, v15, v19, s24
	v_add3_u32 v14, v14, v18, s24
	v_add3_u32 v11, v11, v17, s24
	v_add3_u32 v10, v10, v16, s24
	v_lshrrev_b32_e32 v10, 16, v10
	v_lshrrev_b32_e32 v11, 16, v11
	v_lshrrev_b32_e32 v14, 16, v14
	v_lshrrev_b32_e32 v15, 16, v15
	v_add_u32_e32 v18, s8, v136
	v_and_or_b32 v13, v13, s22, v15
	v_and_or_b32 v12, v12, s22, v14
	v_and_or_b32 v11, v20, s22, v11
	v_and_or_b32 v10, v21, s22, v10
	v_ashrrev_i32_e32 v19, 31, v18
	global_store_dwordx4 v[26:27], v[10:13], off offset:1024
	s_and_b64 vcc, exec, s[0:1]
	s_mov_b64 s[8:9], -1
	v_lshlrev_b64 v[10:11], 11, v[18:19]
	v_lshl_add_u64 v[20:21], s[6:7], 0, v[10:11]
	s_cbranch_vccnz .LBB0_839
	v_lshl_add_u64 v[10:11], v[20:21], 0, v[74:75]
	v_mov_b64_e32 v[14:15], v[214:215]
	v_mov_b64_e32 v[16:17], v[216:217]
	s_cbranch_execz .LBB0_840

.LBB0_838:
	v_mov_b32_e32 v95, v75
	v_lshl_add_u64 v[10:11], v[20:21], 0, v[94:95]
	v_mov_b64_e32 v[10:11], v[218:219]
	v_mov_b64_e32 v[12:13], v[220:221]
	s_cbranch_execnz .LBB0_776
	s_branch .LBB0_842
